# sample-row norm body batched (A1) and attention q-norm gains staged in per-wave LDS (prologue read latency)
# speedup vs baseline: 1.0125x; 1.0034x over previous
.LBB0_194:
	v_lshl_add_u64 v[76:77], s[42:43], 0, v[2:3]
	global_load_dwordx4 v[4:7], v[76:77], off
	global_load_dwordx4 v[8:11], v[76:77], off offset:1024
	global_load_dwordx4 v[12:15], v[76:77], off offset:2048
	global_load_dwordx4 v[16:19], v[76:77], off offset:3072
	s_mov_b64 s[42:43], 0x1000
	v_lshl_add_u64 v[84:85], v[76:77], 0, s[42:43]
	global_load_dwordx4 v[20:23], v[84:85], off
	global_load_dwordx4 v[24:27], v[84:85], off offset:1024
	global_load_dwordx4 v[28:31], v[84:85], off offset:2048
	global_load_dwordx4 v[32:35], v[84:85], off offset:3072
	s_mov_b64 s[42:43], 0x2000
	v_lshl_add_u64 v[86:87], v[76:77], 0, s[42:43]
	global_load_dwordx4 v[36:39], v[86:87], off
	global_load_dwordx4 v[40:43], v[86:87], off offset:1024
	global_load_dwordx4 v[44:47], v[86:87], off offset:2048
	global_load_dwordx4 v[48:51], v[86:87], off offset:3072
	s_mov_b64 s[42:43], 0x3000
	v_lshl_add_u64 v[74:75], v[76:77], 0, s[42:43]
	global_load_dwordx4 v[52:55], v[74:75], off
	global_load_dwordx4 v[56:59], v[74:75], off offset:1024
	global_load_dwordx4 v[60:63], v[74:75], off offset:2048
	global_load_dwordx4 v[64:67], v[74:75], off offset:3072
	s_lshr_b32 s39, s10, 5
	s_add_i32 s42, s39, 4
	s_ashr_i32 s43, s38, 12
	s_and_b64 s[38:39], exec, s[40:41]
	s_cselect_b32 s38, s43, s42
	s_mul_i32 s38, s38, 3
	s_ashr_i32 s39, s38, 31
	s_lshl_b64 s[38:39], s[38:39], 14
	s_lshl_b64 s[36:37], s[36:37], 13
	v_lshl_add_u64 v[112:113], v[68:69], 0, s[38:39]
	s_mov_b64 s[42:43], 0x4000
	v_lshl_add_u64 v[110:111], v[112:113], 0, s[42:43]
	v_lshl_add_u64 v[108:109], v[70:71], 0, s[36:37]
	s_mov_b64 s[42:43], 0x1000
	v_lshl_add_u64 v[106:107], v[108:109], 0, s[42:43]
	global_load_dwordx4 v[116:119], v[112:113], off
	global_load_dwordx4 v[120:123], v[112:113], off offset:1024
	global_load_dwordx4 v[124:127], v[112:113], off offset:2048
	global_load_dwordx4 v[128:131], v[112:113], off offset:3072
	global_load_dwordx4 v[132:135], v[110:111], off
	global_load_dwordx4 v[136:139], v[110:111], off offset:1024
	global_load_dwordx4 v[140:143], v[110:111], off offset:2048
	global_load_dwordx4 v[144:147], v[110:111], off offset:3072
	s_add_i32 s10, s10, s2
	s_add_i32 s36, s10, 0x4000
	s_add_u32 s0, s0, s2
	s_addc_u32 s1, s1, s3
	s_add_u32 s4, s4, s6
	s_addc_u32 s5, s5, s7
	s_waitcnt vmcnt(8)
	v_pk_mul_f32 v[88:89], v[4:5], v[4:5]
	v_pk_fma_f32 v[88:89], v[6:7], v[6:7], v[88:89]
	v_pk_mul_f32 v[90:91], v[8:9], v[8:9]
	v_pk_fma_f32 v[90:91], v[10:11], v[10:11], v[90:91]
	v_pk_add_f32 v[88:89], v[88:89], v[90:91]
	v_pk_mul_f32 v[90:91], v[12:13], v[12:13]
	v_pk_fma_f32 v[90:91], v[14:15], v[14:15], v[90:91]
	v_pk_add_f32 v[88:89], v[88:89], v[90:91]
	v_pk_mul_f32 v[90:91], v[16:17], v[16:17]
	v_pk_fma_f32 v[90:91], v[18:19], v[18:19], v[90:91]
	v_pk_add_f32 v[88:89], v[88:89], v[90:91]
	v_pk_mul_f32 v[90:91], v[20:21], v[20:21]
	v_pk_fma_f32 v[90:91], v[22:23], v[22:23], v[90:91]
	v_pk_add_f32 v[88:89], v[88:89], v[90:91]
	v_pk_mul_f32 v[90:91], v[24:25], v[24:25]
	v_pk_fma_f32 v[90:91], v[26:27], v[26:27], v[90:91]
	v_pk_add_f32 v[88:89], v[88:89], v[90:91]
	v_pk_mul_f32 v[90:91], v[28:29], v[28:29]
	v_pk_fma_f32 v[90:91], v[30:31], v[30:31], v[90:91]
	v_pk_add_f32 v[88:89], v[88:89], v[90:91]
	v_pk_mul_f32 v[90:91], v[32:33], v[32:33]
	v_pk_fma_f32 v[90:91], v[34:35], v[34:35], v[90:91]
	v_pk_add_f32 v[88:89], v[88:89], v[90:91]
	v_pk_mul_f32 v[90:91], v[36:37], v[36:37]
	v_pk_fma_f32 v[90:91], v[38:39], v[38:39], v[90:91]
	v_pk_add_f32 v[88:89], v[88:89], v[90:91]
	v_pk_mul_f32 v[90:91], v[40:41], v[40:41]
	v_pk_fma_f32 v[90:91], v[42:43], v[42:43], v[90:91]
	v_pk_add_f32 v[88:89], v[88:89], v[90:91]
	v_pk_mul_f32 v[90:91], v[44:45], v[44:45]
	v_pk_fma_f32 v[90:91], v[46:47], v[46:47], v[90:91]
	v_pk_add_f32 v[88:89], v[88:89], v[90:91]
	v_pk_mul_f32 v[90:91], v[48:49], v[48:49]
	v_pk_fma_f32 v[90:91], v[50:51], v[50:51], v[90:91]
	v_pk_add_f32 v[88:89], v[88:89], v[90:91]
	v_pk_mul_f32 v[90:91], v[52:53], v[52:53]
	v_pk_fma_f32 v[90:91], v[54:55], v[54:55], v[90:91]
	v_pk_add_f32 v[88:89], v[88:89], v[90:91]
	v_pk_mul_f32 v[90:91], v[56:57], v[56:57]
	v_pk_fma_f32 v[90:91], v[58:59], v[58:59], v[90:91]
	v_pk_add_f32 v[88:89], v[88:89], v[90:91]
	v_pk_mul_f32 v[90:91], v[60:61], v[60:61]
	v_pk_fma_f32 v[90:91], v[62:63], v[62:63], v[90:91]
	v_pk_add_f32 v[88:89], v[88:89], v[90:91]
	v_pk_mul_f32 v[90:91], v[64:65], v[64:65]
	v_pk_fma_f32 v[90:91], v[66:67], v[66:67], v[90:91]
	v_pk_add_f32 v[88:89], v[88:89], v[90:91]
	s_nop 0
	v_add_f32_e32 v72, v88, v89
	ds_bpermute_b32 v74, v73, v72
	s_waitcnt lgkmcnt(0)
	v_add_f32_e32 v72, v72, v74
	ds_bpermute_b32 v74, v78, v72
	s_waitcnt lgkmcnt(0)
	v_add_f32_e32 v72, v72, v74
	ds_bpermute_b32 v74, v79, v72
	s_waitcnt lgkmcnt(0)
	v_add_f32_e32 v72, v72, v74
	ds_bpermute_b32 v74, v80, v72
	s_waitcnt lgkmcnt(0)
	v_add_f32_e32 v72, v72, v74
	ds_bpermute_b32 v74, v81, v72
	s_waitcnt lgkmcnt(0)
	v_add_f32_e32 v72, v72, v74
	ds_bpermute_b32 v74, v82, v72
	s_waitcnt lgkmcnt(0)
	v_add_f32_e32 v72, v72, v74
	v_fmamk_f32 v72, v72, 0x39800000, v1
	v_mul_f32_e32 v74, 0x4b800000, v72
	v_cmp_gt_f32_e32 vcc, s33, v72
	s_nop 1
	v_cndmask_b32_e32 v72, v72, v74, vcc
	v_rsq_f32_e32 v72, v72
	s_nop 0
	v_mul_f32_e32 v74, 0x45800000, v72
	v_cndmask_b32_e32 v72, v72, v74, vcc
	s_mov_b64 s[42:43], 0x1000
	v_lshl_add_u64 v[100:101], v[112:113], 0, s[42:43]
	v_lshl_add_u64 v[104:105], v[110:111], 0, s[42:43]
	global_load_dwordx4 v[206:209], v[100:101], off
	global_load_dwordx4 v[210:213], v[100:101], off offset:1024
	global_load_dwordx4 v[214:217], v[100:101], off offset:2048
	global_load_dwordx4 v[218:221], v[100:101], off offset:3072
	global_load_dwordx4 v[222:225], v[104:105], off
	global_load_dwordx4 v[226:229], v[104:105], off offset:1024
	global_load_dwordx4 v[230:233], v[104:105], off offset:2048
	global_load_dwordx4 v[234:237], v[104:105], off offset:3072
	s_waitcnt vmcnt(8)
	v_pk_mul_f32 v[4:5], v[72:73], v[4:5] op_sel_hi:[0,1]
	v_pk_mul_f32 v[6:7], v[72:73], v[6:7] op_sel_hi:[0,1]
	v_pk_fma_f32 v[4:5], v[116:117], v[4:5], v[132:133]
	v_pk_fma_f32 v[6:7], v[118:119], v[6:7], v[134:135]
	v_cvt_pk_bf16_f32 v4, v4, v5
	v_cvt_pk_bf16_f32 v5, v6, v7
	global_store_dwordx2 v[108:109], v[4:5], off
	v_pk_mul_f32 v[8:9], v[72:73], v[8:9] op_sel_hi:[0,1]
	v_pk_mul_f32 v[10:11], v[72:73], v[10:11] op_sel_hi:[0,1]
	v_pk_fma_f32 v[8:9], v[120:121], v[8:9], v[136:137]
	v_pk_fma_f32 v[10:11], v[122:123], v[10:11], v[138:139]
	v_cvt_pk_bf16_f32 v8, v8, v9
	v_cvt_pk_bf16_f32 v9, v10, v11
	global_store_dwordx2 v[108:109], v[8:9], off offset:512
	v_pk_mul_f32 v[12:13], v[72:73], v[12:13] op_sel_hi:[0,1]
	v_pk_mul_f32 v[14:15], v[72:73], v[14:15] op_sel_hi:[0,1]
	v_pk_fma_f32 v[12:13], v[124:125], v[12:13], v[140:141]
	v_pk_fma_f32 v[14:15], v[126:127], v[14:15], v[142:143]
	v_cvt_pk_bf16_f32 v12, v12, v13
	v_cvt_pk_bf16_f32 v13, v14, v15
	global_store_dwordx2 v[108:109], v[12:13], off offset:1024
	v_pk_mul_f32 v[16:17], v[72:73], v[16:17] op_sel_hi:[0,1]
	v_pk_mul_f32 v[18:19], v[72:73], v[18:19] op_sel_hi:[0,1]
	v_pk_fma_f32 v[16:17], v[128:129], v[16:17], v[144:145]
	v_pk_fma_f32 v[18:19], v[130:131], v[18:19], v[146:147]
	v_cvt_pk_bf16_f32 v16, v16, v17
	v_cvt_pk_bf16_f32 v17, v18, v19
	global_store_dwordx2 v[108:109], v[16:17], off offset:1536
	s_mov_b64 s[42:43], 0x2000
	v_lshl_add_u64 v[100:101], v[112:113], 0, s[42:43]
	v_lshl_add_u64 v[104:105], v[110:111], 0, s[42:43]
	global_load_dwordx4 v[116:119], v[100:101], off
	global_load_dwordx4 v[120:123], v[100:101], off offset:1024
	global_load_dwordx4 v[124:127], v[100:101], off offset:2048
	global_load_dwordx4 v[128:131], v[100:101], off offset:3072
	global_load_dwordx4 v[132:135], v[104:105], off
	global_load_dwordx4 v[136:139], v[104:105], off offset:1024
	global_load_dwordx4 v[140:143], v[104:105], off offset:2048
	global_load_dwordx4 v[144:147], v[104:105], off offset:3072
	s_waitcnt vmcnt(12)
	v_pk_mul_f32 v[20:21], v[72:73], v[20:21] op_sel_hi:[0,1]
	v_pk_mul_f32 v[22:23], v[72:73], v[22:23] op_sel_hi:[0,1]
	v_pk_fma_f32 v[20:21], v[206:207], v[20:21], v[222:223]
	v_pk_fma_f32 v[22:23], v[208:209], v[22:23], v[224:225]
	v_cvt_pk_bf16_f32 v20, v20, v21
	v_cvt_pk_bf16_f32 v21, v22, v23
	global_store_dwordx2 v[108:109], v[20:21], off offset:2048
	v_pk_mul_f32 v[24:25], v[72:73], v[24:25] op_sel_hi:[0,1]
	v_pk_mul_f32 v[26:27], v[72:73], v[26:27] op_sel_hi:[0,1]
	v_pk_fma_f32 v[24:25], v[210:211], v[24:25], v[226:227]
	v_pk_fma_f32 v[26:27], v[212:213], v[26:27], v[228:229]
	v_cvt_pk_bf16_f32 v24, v24, v25
	v_cvt_pk_bf16_f32 v25, v26, v27
	global_store_dwordx2 v[108:109], v[24:25], off offset:2560
	v_pk_mul_f32 v[28:29], v[72:73], v[28:29] op_sel_hi:[0,1]
	v_pk_mul_f32 v[30:31], v[72:73], v[30:31] op_sel_hi:[0,1]
	v_pk_fma_f32 v[28:29], v[214:215], v[28:29], v[230:231]
	v_pk_fma_f32 v[30:31], v[216:217], v[30:31], v[232:233]
	v_cvt_pk_bf16_f32 v28, v28, v29
	v_cvt_pk_bf16_f32 v29, v30, v31
	global_store_dwordx2 v[108:109], v[28:29], off offset:3072
	v_pk_mul_f32 v[32:33], v[72:73], v[32:33] op_sel_hi:[0,1]
	v_pk_mul_f32 v[34:35], v[72:73], v[34:35] op_sel_hi:[0,1]
	v_pk_fma_f32 v[32:33], v[218:219], v[32:33], v[234:235]
	v_pk_fma_f32 v[34:35], v[220:221], v[34:35], v[236:237]
	v_cvt_pk_bf16_f32 v32, v32, v33
	v_cvt_pk_bf16_f32 v33, v34, v35
	global_store_dwordx2 v[108:109], v[32:33], off offset:3584
	s_mov_b64 s[42:43], 0x3000
	v_lshl_add_u64 v[100:101], v[112:113], 0, s[42:43]
	v_lshl_add_u64 v[104:105], v[110:111], 0, s[42:43]
	global_load_dwordx4 v[206:209], v[100:101], off
	global_load_dwordx4 v[210:213], v[100:101], off offset:1024
	global_load_dwordx4 v[214:217], v[100:101], off offset:2048
	global_load_dwordx4 v[218:221], v[100:101], off offset:3072
	global_load_dwordx4 v[222:225], v[104:105], off
	global_load_dwordx4 v[226:229], v[104:105], off offset:1024
	global_load_dwordx4 v[230:233], v[104:105], off offset:2048
	global_load_dwordx4 v[234:237], v[104:105], off offset:3072
	s_waitcnt vmcnt(12)
	v_pk_mul_f32 v[36:37], v[72:73], v[36:37] op_sel_hi:[0,1]
	v_pk_mul_f32 v[38:39], v[72:73], v[38:39] op_sel_hi:[0,1]
	v_pk_fma_f32 v[36:37], v[116:117], v[36:37], v[132:133]
	v_pk_fma_f32 v[38:39], v[118:119], v[38:39], v[134:135]
	v_cvt_pk_bf16_f32 v36, v36, v37
	v_cvt_pk_bf16_f32 v37, v38, v39
	global_store_dwordx2 v[106:107], v[36:37], off
	v_pk_mul_f32 v[40:41], v[72:73], v[40:41] op_sel_hi:[0,1]
	v_pk_mul_f32 v[42:43], v[72:73], v[42:43] op_sel_hi:[0,1]
	v_pk_fma_f32 v[40:41], v[120:121], v[40:41], v[136:137]
	v_pk_fma_f32 v[42:43], v[122:123], v[42:43], v[138:139]
	v_cvt_pk_bf16_f32 v40, v40, v41
	v_cvt_pk_bf16_f32 v41, v42, v43
	global_store_dwordx2 v[106:107], v[40:41], off offset:512
	v_pk_mul_f32 v[44:45], v[72:73], v[44:45] op_sel_hi:[0,1]
	v_pk_mul_f32 v[46:47], v[72:73], v[46:47] op_sel_hi:[0,1]
	v_pk_fma_f32 v[44:45], v[124:125], v[44:45], v[140:141]
	v_pk_fma_f32 v[46:47], v[126:127], v[46:47], v[142:143]
	v_cvt_pk_bf16_f32 v44, v44, v45
	v_cvt_pk_bf16_f32 v45, v46, v47
	global_store_dwordx2 v[106:107], v[44:45], off offset:1024
	v_pk_mul_f32 v[48:49], v[72:73], v[48:49] op_sel_hi:[0,1]
	v_pk_mul_f32 v[50:51], v[72:73], v[50:51] op_sel_hi:[0,1]
	v_pk_fma_f32 v[48:49], v[128:129], v[48:49], v[144:145]
	v_pk_fma_f32 v[50:51], v[130:131], v[50:51], v[146:147]
	v_cvt_pk_bf16_f32 v48, v48, v49
	v_cvt_pk_bf16_f32 v49, v50, v51
	global_store_dwordx2 v[106:107], v[48:49], off offset:1536
	s_waitcnt vmcnt(4)
	v_pk_mul_f32 v[52:53], v[72:73], v[52:53] op_sel_hi:[0,1]
	v_pk_mul_f32 v[54:55], v[72:73], v[54:55] op_sel_hi:[0,1]
	v_pk_fma_f32 v[52:53], v[206:207], v[52:53], v[222:223]
	v_pk_fma_f32 v[54:55], v[208:209], v[54:55], v[224:225]
	v_cvt_pk_bf16_f32 v52, v52, v53
	v_cvt_pk_bf16_f32 v53, v54, v55
	global_store_dwordx2 v[106:107], v[52:53], off offset:2048
	v_pk_mul_f32 v[56:57], v[72:73], v[56:57] op_sel_hi:[0,1]
	v_pk_mul_f32 v[58:59], v[72:73], v[58:59] op_sel_hi:[0,1]
	v_pk_fma_f32 v[56:57], v[210:211], v[56:57], v[226:227]
	v_pk_fma_f32 v[58:59], v[212:213], v[58:59], v[228:229]
	v_cvt_pk_bf16_f32 v56, v56, v57
	v_cvt_pk_bf16_f32 v57, v58, v59
	global_store_dwordx2 v[106:107], v[56:57], off offset:2560
	v_pk_mul_f32 v[60:61], v[72:73], v[60:61] op_sel_hi:[0,1]
	v_pk_mul_f32 v[62:63], v[72:73], v[62:63] op_sel_hi:[0,1]
	v_pk_fma_f32 v[60:61], v[214:215], v[60:61], v[230:231]
	v_pk_fma_f32 v[62:63], v[216:217], v[62:63], v[232:233]
	v_cvt_pk_bf16_f32 v60, v60, v61
	v_cvt_pk_bf16_f32 v61, v62, v63
	global_store_dwordx2 v[106:107], v[60:61], off offset:3072
	v_pk_mul_f32 v[64:65], v[72:73], v[64:65] op_sel_hi:[0,1]
	v_pk_mul_f32 v[66:67], v[72:73], v[66:67] op_sel_hi:[0,1]
	v_pk_fma_f32 v[64:65], v[218:219], v[64:65], v[234:235]
	v_pk_fma_f32 v[66:67], v[220:221], v[66:67], v[236:237]
	v_cvt_pk_bf16_f32 v64, v64, v65
	v_cvt_pk_bf16_f32 v65, v66, v67
	global_store_dwordx2 v[106:107], v[64:65], off offset:3584
	s_cmpk_lt_i32 s36, 0x4200
	s_cbranch_scc0 .LBB0_197

; __global__ void __launch_bounds__(NWAVES * 64, 2) mk_fwd(Args args) {
;     ...
;         if (IN(pb + 5) && EN(7)) {
;             PHASE_LOCALS
;             const float* gqn = args.in[28] + (size_t)l * 128; const float* gqr = args.in[29] + (size_t)l * ROPE;
;             for (int v = bx; v < 256; v += G) {
;                 const int vv = (G == 256) ? ((v & 7) * 32 + (v >> 3)) : v;
;                 const int bh = vv >> 2, s = vv & 3, b = bh >> 4, h = bh & 15;
; #pragma unroll 1
;                 for (int i = 0; i < 4; ++i) {
;                     const int qb = (i == 0) ? 15 - s : (i == 1) ? s : (i == 2) ? 11 - s : 4 + s;
;                     const size_t m0 = (size_t)b * SEQ + (size_t)qb * 256, k0 = (size_t)b * SEQ;
;                     att::AUnit u{Qb + m0 * QW + h * 192, Kn + ((size_t)h * KROWS + k0) * 128, Vb + ((size_t)h * KROWS + k0) * 128, Krb + k0 * ROPE, hmix + m0 * DM + RW + h * 128, 4 * qb + 4, 8, 4 * qb, 0, qb * 256, gqn, gqr, tab};
.LBB0_927:
	s_andn2_b64 vcc, exec, s[0:1]
	s_cbranch_vccnz .LBB0_1313
	s_waitcnt lgkmcnt(0)
	v_mov_b32_e32 v2, v0
	s_mov_b64 s[0:1], 0
	v_readlane_b32 s62, v252, 3
	v_readlane_b32 s63, v252, 0
	s_cmpk_gt_i32 s63, 0xff
	s_cbranch_scc1 .LBB0_1259
	v_readlane_b32 s2, v252, 12
	v_readlane_b32 s3, v252, 13
	s_add_u32 s2, s2, s0
	s_addc_u32 s3, s3, s1
	s_add_u32 s6, s2, 0x100000
	s_addc_u32 s7, s3, 0
	s_add_u32 s64, s2, 0xaf00000
	s_addc_u32 s65, s3, 0
	s_add_u32 s66, s2, 0x13300000
	s_addc_u32 s67, s3, 0
	s_add_u32 s68, s2, 0x1f500000
	s_addc_u32 s69, s3, 0
	s_add_u32 s70, s2, 0x44400000
	v_readlane_b32 s4, v254, 54
	s_addc_u32 s71, s3, 0
	v_readlane_b32 s5, v254, 55
	v_readlane_b32 s76, v252, 18
	s_add_u32 s72, s2, 0x4d800000
	s_mov_b32 s5, s11
	v_readlane_b32 s84, v252, 26
	v_readlane_b32 s85, v252, 27
	s_addc_u32 s73, s3, 0
	s_lshl_b64 s[2:3], s[4:5], 9
	v_readlane_b32 s86, v252, 28
	v_readlane_b32 s87, v252, 29
	v_readlane_b32 s88, v252, 30
	v_readlane_b32 s89, v252, 31
	v_readlane_b32 s90, v252, 32
	v_readlane_b32 s91, v252, 33
	s_mov_b64 s[48:49], s[84:85]
	s_add_u32 s8, s48, s2
	s_mov_b64 s[50:51], s[86:87]
	s_addc_u32 s9, s49, s3
	s_lshl_b64 s[2:3], s[4:5], 8
	s_add_u32 s36, s50, s2
	s_addc_u32 s37, s51, s3
	s_cmpk_eq_i32 s62, 0x100
	s_cselect_b64 s[38:39], -1, 0
	s_mov_b32 s74, s63
	v_readlane_b32 s77, v252, 19
	v_readlane_b32 s78, v252, 20
	v_readlane_b32 s79, v252, 21
	v_readlane_b32 s80, v252, 22
	v_readlane_b32 s81, v252, 23
	v_readlane_b32 s82, v252, 24
	v_readlane_b32 s83, v252, 25
	s_mov_b64 s[52:53], s[88:89]
	s_mov_b64 s[54:55], s[90:91]
	v_and_b32_e32 v2, 63, v0
	v_lshlrev_b32_e32 v2, 2, v2
	global_load_dword v4, v2, s[8:9]
	global_load_dword v5, v2, s[8:9] offset:256
	global_load_dword v227, v2, s[36:37]
	v_lshrrev_b32_e32 v228, 6, v0
	v_lshl_add_u32 v228, v228, 10, v2
	v_add_u32_e32 v228, 0x15000, v228
	s_waitcnt vmcnt(0)
	ds_write_b32 v228, v4
	ds_write_b32 v228, v5 offset:256
	ds_write_b32 v228, v227 offset:512
	s_waitcnt lgkmcnt(0)
	s_branch .LBB0_932

; template <int VAR>
; __device__ __forceinline__ void attn_unit(const AUnit& u, LAS char* lds) {
;     ...
;     const bool wact = wid < u.nwav;
;     const int jmax = u.jbase + (wid >> 1);
;     const bf16_t* gk0; const bf16_t* gk1; const bf16_t* gkr; const bf16_t* gv0; const bf16_t* gv1;
;     {
;         const int rk0 = (2 * wid) * 4 + (lane >> 4), rk1 = rk0 + 4, ph = lane & 15;
;         gk0 = u.Kn + (size_t)rk0 * 128 + ((ph ^ (rk0 & 15)) * 8);
;         gk1 = u.Kn + (size_t)rk1 * 128 + ((ph ^ (rk1 & 15)) * 8);
;         const int rr0 = wid * 8 + (lane >> 3), pr = lane & 7;
;         gkr = u.Kr + (size_t)rr0 * ROPE + ((pr ^ ((rr0 >> 1) & 7)) * 8);
; #pragma unroll
;         for (int i = 0; i < 2; ++i) {
;             const int st = (2 * wid + i) * 2 + (lane >> 5), o16 = lane & 31, kk = (st >> 2) * 8 + (o16 >> 2), c = (st & 3) * 32 + (o16 & 3) * 8;
;             const int key = (kk & ~0xC) | ((kk & 4) << 1) | ((kk & 8) >> 1);
;             const bf16_t* p = u.V + (size_t)key * 128 + c;
;             if (i == 0) gv0 = p; else gv1 = p;
;         }
;     }
;     ...
;     ADMA(0, 0);
;     bf16x8 qr[12];
;     {
;         const int wq = wact ? wid : 0;
;         const bf16_t* qp = u.Q + (size_t)(wq * 32 + r32) * QW + hi * 8;
; #pragma unroll
;         for (int d0 = 0; d0 < 12; ++d0) qr[d0] = *(const bf16x8*)(qp + d0 * 16);
.LBB0_941:
	s_lshl_b64 s[2:3], s[10:11], 8
	s_add_u32 s54, s2, s40
	s_addc_u32 s55, s3, s41
	s_mul_i32 s2, s55, 0x1800
	s_mul_hi_u32 s3, s54, 0x1800
	s_add_i32 s3, s3, s2
	s_mul_i32 s2, s54, 0x1800
	v_mov_b32_e32 v181, v0
	s_add_u32 s2, s76, s2
	s_addc_u32 s3, s77, s3
	v_readfirstlane_b32 s5, v181
	s_ashr_i32 s19, s5, 6
	s_lshl_b32 s56, s19, 3
	s_waitcnt lgkmcnt(0)
	v_bfe_u32 v2, v181, 4, 2
	s_waitcnt vmcnt(0)
	v_or_b32_e32 v4, s56, v2
	v_and_b32_e32 v2, 15, v181
	v_ashrrev_i32_e32 v5, 31, v4
	v_bitop3_b32 v10, v4, v2, 11 bitop3:0x6c
	v_bfe_u32 v2, v181, 3, 3
	v_or_b32_e32 v32, 4, v4
	v_lshlrev_b64 v[36:37], 8, v[4:5]
	v_bitop3_b32 v12, v4, v181, 4 bitop3:0x36
	v_or_b32_e32 v4, s56, v2
	v_ashrrev_i32_e32 v33, 31, v32
	v_ashrrev_i32_e32 v5, 31, v4
	v_bfe_u32 v2, v181, 2, 3
	v_lshlrev_b64 v[34:35], 8, v[32:33]
	v_lshlrev_b64 v[38:39], 7, v[4:5]
	v_lshrrev_b32_e32 v33, 1, v4
	v_bitop3_b32 v2, s56, -13, v2 bitop3:0xc8
	v_lshrrev_b32_e32 v4, 1, v181
	s_lshl_b32 s56, s19, 2
	v_and_b32_e32 v4, 8, v4
	s_and_b32 s56, s56, 4
	v_or3_b32 v4, v2, v4, s56
	s_lshl_b32 s56, s19, 11
	s_add_i32 s84, s56, 0
	s_lshl_b32 s56, s19, 10
	s_lshl_b32 s4, s10, 2
	s_add_i32 s87, s56, 0
	s_add_i32 s57, s4, 4
	s_ashr_i32 s91, s5, 7
	v_xor_b32_e32 v14, v33, v181
	s_add_i32 s85, s84, 0x8000
	s_add_i32 s86, s84, 0x8400
	s_add_i32 s88, s87, 0xc000
	s_add_i32 s89, s84, 0x400
	s_lshl_b32 s56, s19, 5
	v_lshl_add_u64 v[8:9], s[42:43], 0, v[36:37]
	v_lshlrev_b32_e32 v42, 4, v10
	v_mov_b32_e32 v43, v3
	v_lshlrev_b32_e32 v12, 4, v12
	v_and_b32_e32 v90, 32, v181
	v_lshrrev_b32_e32 v248, 6, v181
	v_lshl_add_u32 v248, v248, 10, v90
	v_add_u32_e32 v248, 0x15000, v248
	v_lshlrev_b32_e32 v89, 3, v181
	v_ashrrev_i32_e32 v5, 31, v4
	s_cmp_lt_i32 s19, 8
	v_lshl_add_u64 v[8:9], v[8:9], 0, v[42:43]
	v_lshl_add_u64 v[10:11], s[42:43], 0, v[34:35]
	v_and_b32_e32 v12, 0xf0, v12
	v_mov_b32_e32 v13, v3
	v_lshlrev_b32_e32 v14, 4, v14
	s_mov_b32 m0, s85
	v_and_or_b32 v6, v89, 24, v90
	v_lshlrev_b64 v[40:41], 8, v[4:5]
	s_cselect_b64 s[58:59], -1, 0
	v_lshl_add_u64 v[10:11], v[10:11], 0, v[12:13]
	v_lshl_add_u64 v[12:13], s[48:49], 0, v[38:39]
	v_and_b32_e32 v14, 0x70, v14
	v_mov_b32_e32 v15, v3
	global_load_lds_dwordx4 v[8:9], off
	s_mov_b32 m0, s86
	v_lshl_add_u64 v[4:5], s[46:47], 0, v[40:41]
	v_lshlrev_b32_e32 v2, 1, v6
	v_lshl_add_u64 v[12:13], v[12:13], 0, v[14:15]
	global_load_lds_dwordx4 v[10:11], off
	s_mov_b32 m0, s88
	s_and_b64 s[60:61], s[58:59], exec
	v_and_b32_e32 v180, 31, v181
	v_lshl_add_u64 v[4:5], v[4:5], 0, v[2:3]
	global_load_lds_dwordx4 v[12:13], off
	s_mov_b32 m0, s84
	s_cselect_b32 s60, s56, 0
	v_lshl_add_u64 v[6:7], v[4:5], 0, s[28:29]
	v_bfe_u32 v182, v181, 5, 1
	global_load_lds_dwordx4 v[4:5], off
	v_or_b32_e32 v43, s60, v180
	v_mov_b64_e32 v[4:5], s[2:3]
	s_mov_b32 m0, s89
	v_mad_i64_i32 v[4:5], s[2:3], v43, s45, v[4:5]
	v_lshlrev_b32_e32 v162, 4, v182
	v_mov_b32_e32 v163, v3
	global_load_lds_dwordx4 v[6:7], off
	v_lshl_add_u64 v[8:9], v[4:5], 0, v[162:163]
	global_load_dwordx4 v[28:31], v[8:9], off
	global_load_dwordx4 v[24:27], v[8:9], off offset:32
	global_load_dwordx4 v[20:23], v[8:9], off offset:64
	global_load_dwordx4 v[44:47], v[8:9], off offset:96
	global_load_dwordx4 v[48:51], v[8:9], off offset:128
	global_load_dwordx4 v[52:55], v[8:9], off offset:160
	global_load_dwordx4 v[108:111], v[8:9], off offset:192
	global_load_dwordx4 v[112:115], v[8:9], off offset:224
	global_load_dwordx4 v[12:15], v[8:9], off offset:256
	global_load_dwordx4 v[4:7], v[8:9], off offset:288
	global_load_dwordx4 v[16:19], v[8:9], off offset:320
	s_nop 0
	global_load_dwordx4 v[8:11], v[8:9], off offset:352
	s_lshl_b32 s2, s10, 13
	v_lshl_add_u32 v43, v43, 5, s2
	v_and_b32_e32 v88, 63, v181
	v_lshl_add_u32 v183, v180, 8, 0
	s_add_i32 s10, 0, 0x12000
	s_and_b32 s2, s5, 0x3fffffc0
	s_lshl_b32 s2, s2, 2
	s_add_i32 s90, s2, 0
	v_or_b32_e32 v36, v36, v42
	v_or_b32_e32 v40, v40, v2
	s_add_i32 s90, s90, 0x14000
	v_lshl_add_u64 v[172:173], s[50:51], 0, v[36:37]
	v_lshl_add_u64 v[178:179], s[50:51], 0, v[40:41]
	v_mov_b32_e32 v2, v3
	s_mov_b32 s19, 0
	s_add_i32 s91, s91, s4
	v_bitop3_b32 v212, v162, v89, s21 bitop3:0x78
	v_cmp_gt_u32_e64 s[2:3], 32, v88
	v_lshl_add_u32 v206, v180, 2, s90
	v_mov_b32_e32 v225, 0
	v_mov_b32_e32 v226, 0xf149f2ca
	s_waitcnt vmcnt(0)
; __device__ __forceinline__ u32x4 pack8(const float* f) { u32x4 w; w.x = cvtpk(f[0], f[1]); w.y = cvtpk(f[2], f[3]); w.z = cvtpk(f[4], f[5]); w.w = cvtpk(f[6], f[7]); return w; }
; __device__ __forceinline__ bf16x8 pack8(const f32x4& a, const f32x4& b) { u32x4 w; w.x = cpk(a.x, a.y); w.y = cpk(a.z, a.w); w.z = cpk(b.x, b.y); w.w = cpk(b.z, b.w); return __builtin_bit_cast(bf16x8, w); }
; template <int VAR>
; __device__ __forceinline__ void attn_unit(const AUnit& u, LAS char* lds) {
;     ...
;         float ssn = 0.f, ssr = 0.f;
; #pragma unroll
;         for (int d0 = 0; d0 < 12; ++d0) { float f[8]; unpack8(__builtin_bit_cast(u32x4, qr[d0]), f); float a = 0.f;
; #pragma unroll
;             for (int e = 0; e < 8; ++e) a += f[e] * f[e];
;             if (d0 < 8) ssn += a; else ssr += a; }
;         { auto rr = __builtin_amdgcn_permlane32_swap(__float_as_uint(ssn), __float_as_uint(ssn), false, false); ssn = __uint_as_float(rr[0]) + __uint_as_float(rr[1]); }
;         { auto rr = __builtin_amdgcn_permlane32_swap(__float_as_uint(ssr), __float_as_uint(ssr), false, false); ssr = __uint_as_float(rr[0]) + __uint_as_float(rr[1]); }
;         const float rn = rsqrtf(ssn * (1.f / 128) + NORM_EPS) * QSCALE, rr_ = rsqrtf(ssr * (1.f / ROPE) + NORM_EPS);
; #pragma unroll
;         for (int d0 = 0; d0 < 8; ++d0) { float f[8]; unpack8(__builtin_bit_cast(u32x4, qr[d0]), f);
;             const f32x4 g0 = *(const f32x4*)(u.gqn + d0 * 16 + hi * 8), g1 = *(const f32x4*)(u.gqn + d0 * 16 + hi * 8 + 4);
; #pragma unroll
;             for (int e = 0; e < 4; ++e) { f[e] *= rn * g0[e]; f[4 + e] *= rn * g1[e]; }
;             qr[d0] = __builtin_bit_cast(bf16x8, pack8(f)); }
	v_and_b32_e32 v104, 0xffff0000, v28
	v_and_b32_e32 v96, 0xffff0000, v24
	v_lshlrev_b32_e32 v106, 16, v28
	v_mul_f32_e32 v28, v104, v104
	v_lshlrev_b32_e32 v100, 16, v24
	v_mul_f32_e32 v24, v96, v96
	v_and_b32_e32 v79, 0xffff0000, v44
	v_and_b32_e32 v78, 0xffff0000, v20
	v_lshlrev_b32_e32 v101, 16, v29
	v_fmac_f32_e32 v28, v106, v106
	v_lshlrev_b32_e32 v94, 16, v25
	v_fmac_f32_e32 v24, v100, v100
	v_lshlrev_b32_e32 v83, 16, v44
	v_lshlrev_b32_e32 v82, 16, v20
	v_lshlrev_b32_e32 v76, 16, v21
	v_and_b32_e32 v74, 0xffff0000, v21
	v_pk_mul_f32 v[20:21], v[78:79], v[78:79]
	v_and_b32_e32 v97, 0xffff0000, v29
	v_fmac_f32_e32 v28, v101, v101
	v_and_b32_e32 v92, 0xffff0000, v25
	v_fmac_f32_e32 v24, v94, v94
	v_lshlrev_b32_e32 v77, 16, v45
	v_pk_fma_f32 v[20:21], v[82:83], v[82:83], v[20:21]
	v_lshlrev_b32_e32 v107, 16, v30
	v_fmac_f32_e32 v28, v97, v97
	v_lshlrev_b32_e32 v102, 16, v26
	v_fmac_f32_e32 v24, v92, v92
	v_and_b32_e32 v75, 0xffff0000, v45
	v_pk_fma_f32 v[20:21], v[76:77], v[76:77], v[20:21]
	v_and_b32_e32 v105, 0xffff0000, v30
	v_fmac_f32_e32 v28, v107, v107
	v_and_b32_e32 v98, 0xffff0000, v26
	v_fmac_f32_e32 v24, v102, v102
	v_lshlrev_b32_e32 v87, 16, v46
	v_lshlrev_b32_e32 v86, 16, v22
	v_pk_fma_f32 v[20:21], v[74:75], v[74:75], v[20:21]
	v_lshlrev_b32_e32 v103, 16, v31
	v_fmac_f32_e32 v28, v105, v105
	v_lshlrev_b32_e32 v95, 16, v27
	v_fmac_f32_e32 v24, v98, v98
	v_and_b32_e32 v85, 0xffff0000, v46
	v_and_b32_e32 v84, 0xffff0000, v22
	v_pk_fma_f32 v[20:21], v[86:87], v[86:87], v[20:21]
	v_and_b32_e32 v99, 0xffff0000, v31
	v_fmac_f32_e32 v28, v103, v103
	v_and_b32_e32 v93, 0xffff0000, v27
	v_fmac_f32_e32 v24, v95, v95
	v_lshlrev_b32_e32 v81, 16, v47
	v_lshlrev_b32_e32 v80, 16, v23
	v_pk_fma_f32 v[20:21], v[84:85], v[84:85], v[20:21]
	v_fmac_f32_e32 v28, v99, v99
	v_fmac_f32_e32 v24, v93, v93
	v_and_b32_e32 v73, 0xffff0000, v47
	v_and_b32_e32 v72, 0xffff0000, v23
	v_pk_fma_f32 v[20:21], v[80:81], v[80:81], v[20:21]
	v_add_f32_e32 v24, v28, v24
	v_pk_fma_f32 v[20:21], v[72:73], v[72:73], v[20:21]
	v_and_b32_e32 v65, 0xffff0000, v52
	v_add_f32_e32 v20, v24, v20
	v_and_b32_e32 v64, 0xffff0000, v48
	v_add_f32_e32 v22, v20, v21
	v_lshlrev_b32_e32 v69, 16, v52
	v_lshlrev_b32_e32 v68, 16, v48
	v_pk_mul_f32 v[20:21], v[64:65], v[64:65]
	v_lshlrev_b32_e32 v61, 16, v53
	v_lshlrev_b32_e32 v60, 16, v49
	v_pk_fma_f32 v[20:21], v[68:69], v[68:69], v[20:21]
	v_and_b32_e32 v59, 0xffff0000, v53
	v_and_b32_e32 v58, 0xffff0000, v49
	v_pk_fma_f32 v[20:21], v[60:61], v[60:61], v[20:21]
	v_lshlrev_b32_e32 v71, 16, v54
	v_lshlrev_b32_e32 v70, 16, v50
	v_pk_fma_f32 v[20:21], v[58:59], v[58:59], v[20:21]
	v_and_b32_e32 v67, 0xffff0000, v54
	v_and_b32_e32 v66, 0xffff0000, v50
	v_pk_fma_f32 v[20:21], v[70:71], v[70:71], v[20:21]
	v_lshlrev_b32_e32 v63, 16, v55
	v_lshlrev_b32_e32 v62, 16, v51
	v_pk_fma_f32 v[20:21], v[66:67], v[66:67], v[20:21]
	v_and_b32_e32 v57, 0xffff0000, v55
	v_and_b32_e32 v56, 0xffff0000, v51
	v_pk_fma_f32 v[20:21], v[62:63], v[62:63], v[20:21]
	v_and_b32_e32 v45, 0xffff0000, v112
	v_pk_fma_f32 v[20:21], v[56:57], v[56:57], v[20:21]
	v_and_b32_e32 v44, 0xffff0000, v108
	v_add_f32_e32 v20, v22, v20
	v_add_f32_e32 v22, v20, v21
	v_lshlrev_b32_e32 v49, 16, v112
	v_lshlrev_b32_e32 v48, 16, v108
	v_pk_mul_f32 v[20:21], v[44:45], v[44:45]
	v_lshlrev_b32_e32 v31, 16, v113
	v_lshlrev_b32_e32 v30, 16, v109
	v_pk_fma_f32 v[20:21], v[48:49], v[48:49], v[20:21]
	v_and_b32_e32 v29, 0xffff0000, v113
	v_and_b32_e32 v28, 0xffff0000, v109
	v_pk_fma_f32 v[20:21], v[30:31], v[30:31], v[20:21]
	v_lshlrev_b32_e32 v55, 16, v114
	v_lshlrev_b32_e32 v54, 16, v110
	v_pk_fma_f32 v[20:21], v[28:29], v[28:29], v[20:21]
	v_and_b32_e32 v53, 0xffff0000, v114
	v_and_b32_e32 v52, 0xffff0000, v110
	v_pk_fma_f32 v[20:21], v[54:55], v[54:55], v[20:21]
	v_lshlrev_b32_e32 v51, 16, v115
	v_lshlrev_b32_e32 v50, 16, v111
	v_pk_fma_f32 v[20:21], v[52:53], v[52:53], v[20:21]
	v_and_b32_e32 v47, 0xffff0000, v115
	v_and_b32_e32 v46, 0xffff0000, v111
	v_pk_fma_f32 v[20:21], v[50:51], v[50:51], v[20:21]
	s_nop 0
	v_pk_fma_f32 v[20:21], v[46:47], v[46:47], v[20:21]
	s_nop 0
	v_add_f32_e32 v20, v22, v20
	v_add_f32_e32 v20, v20, v21
	v_mov_b32_e32 v21, v20
	s_nop 1
	v_permlane32_swap_b32_e32 v20, v21
	v_add_f32_e32 v20, v20, v21
	v_fmamk_f32 v20, v20, 0x3c000000, v1
	v_cmp_gt_f32_e32 vcc, s33, v20
	v_mul_f32_e32 v21, 0x4b800000, v20
	s_nop 0
	v_cndmask_b32_e32 v20, v20, v21, vcc
	v_rsq_f32_e32 v20, v20
	s_nop 0
	v_mul_f32_e32 v21, 0x45800000, v20
	v_cndmask_b32_e32 v20, v20, v21, vcc
	v_mul_f32_e32 v91, 0x3dd53b94, v20
	ds_read_b128 v[20:23], v248 offset:16
	ds_read_b128 v[24:27], v248
	s_waitcnt lgkmcnt(0)
	v_mul_f32_e32 v20, v20, v91
	v_mul_f32_e32 v24, v24, v91
	v_mul_f32_e32 v25, v25, v91
	v_mul_f32_e32 v21, v21, v91
	v_mul_f32_e32 v26, v26, v91
	v_mul_f32_e32 v22, v22, v91
	v_mul_f32_e32 v27, v27, v91
	v_mul_f32_e32 v23, v23, v91
	v_mul_f32_e32 v24, v24, v106
	v_mul_f32_e32 v20, v20, v107
	v_mul_f32_e32 v25, v25, v104
	v_mul_f32_e32 v21, v21, v105
	v_mul_f32_e32 v26, v26, v101
	v_mul_f32_e32 v22, v22, v103
	v_mul_f32_e32 v27, v27, v97
	v_mul_f32_e32 v23, v23, v99
	v_cvt_pk_bf16_f32 v114, v24, v25
	v_cvt_pk_bf16_f32 v115, v26, v27
	v_cvt_pk_bf16_f32 v116, v20, v21
	v_cvt_pk_bf16_f32 v117, v22, v23
	ds_read_b128 v[20:23], v248 offset:80
	ds_read_b128 v[24:27], v248 offset:64
	v_and_b32_e32 v101, 0xffff0000, v8
	v_mov_b32_e32 v103, v101
	v_lshlrev_b32_e32 v97, 16, v9
	v_and_b32_e32 v99, 0xffff0000, v9
	s_waitcnt lgkmcnt(0)
; __device__ __forceinline__ u32x4 pack8(const float* f) { u32x4 w; w.x = cvtpk(f[0], f[1]); w.y = cvtpk(f[2], f[3]); w.z = cvtpk(f[4], f[5]); w.w = cvtpk(f[6], f[7]); return w; }
; __device__ __forceinline__ bf16x8 pack8(const f32x4& a, const f32x4& b) { u32x4 w; w.x = cpk(a.x, a.y); w.y = cpk(a.z, a.w); w.z = cpk(b.x, b.y); w.w = cpk(b.z, b.w); return __builtin_bit_cast(bf16x8, w); }
; template <int VAR>
; __device__ __forceinline__ void attn_unit(const AUnit& u, LAS char* lds) {
;     ...
;         for (int d0 = 0; d0 < 8; ++d0) { float f[8]; unpack8(__builtin_bit_cast(u32x4, qr[d0]), f);
;             const f32x4 g0 = *(const f32x4*)(u.gqn + d0 * 16 + hi * 8), g1 = *(const f32x4*)(u.gqn + d0 * 16 + hi * 8 + 4);
; #pragma unroll
;             for (int e = 0; e < 4; ++e) { f[e] *= rn * g0[e]; f[4 + e] *= rn * g1[e]; }
;             qr[d0] = __builtin_bit_cast(bf16x8, pack8(f)); }
	v_mul_f32_e32 v20, v20, v91
	v_mul_f32_e32 v24, v24, v91
	v_mul_f32_e32 v25, v25, v91
	v_mul_f32_e32 v21, v21, v91
	v_mul_f32_e32 v26, v26, v91
	v_mul_f32_e32 v22, v22, v91
	v_mul_f32_e32 v27, v27, v91
	v_mul_f32_e32 v23, v23, v91
	v_mul_f32_e32 v24, v24, v100
	v_mul_f32_e32 v20, v20, v102
	v_mul_f32_e32 v25, v25, v96
	v_mul_f32_e32 v21, v21, v98
	v_mul_f32_e32 v26, v26, v94
	v_mul_f32_e32 v22, v22, v95
	v_mul_f32_e32 v27, v27, v92
	v_mul_f32_e32 v23, v23, v93
	v_cvt_pk_bf16_f32 v118, v24, v25
	v_cvt_pk_bf16_f32 v119, v26, v27
	v_cvt_pk_bf16_f32 v120, v20, v21
	v_cvt_pk_bf16_f32 v121, v22, v23
	ds_read_b128 v[20:23], v248 offset:144
	ds_read_b128 v[24:27], v248 offset:128
	v_and_b32_e32 v100, 0xffff0000, v4
	v_lshlrev_b32_e32 v96, 16, v5
	v_and_b32_e32 v98, 0xffff0000, v5
	v_lshlrev_b32_e32 v92, 16, v6
	v_and_b32_e32 v94, 0xffff0000, v6
	v_mov_b32_e32 v9, v92
	v_lshlrev_b32_e32 v93, 16, v10
	v_and_b32_e32 v95, 0xffff0000, v10
	s_waitcnt lgkmcnt(0)
	v_mul_f32_e32 v20, v91, v20
	v_mul_f32_e32 v24, v91, v24
	v_mul_f32_e32 v25, v91, v25
	v_mul_f32_e32 v21, v91, v21
	v_mul_f32_e32 v26, v91, v26
	v_mul_f32_e32 v22, v91, v22
	v_mul_f32_e32 v27, v91, v27
	v_mul_f32_e32 v23, v91, v23
	v_mul_f32_e32 v24, v24, v82
	v_mul_f32_e32 v20, v20, v86
	v_mul_f32_e32 v25, v25, v78
	v_mul_f32_e32 v21, v21, v84
	v_mul_f32_e32 v26, v26, v76
	v_mul_f32_e32 v22, v22, v80
	v_mul_f32_e32 v27, v27, v74
	v_mul_f32_e32 v23, v23, v72
	v_cvt_pk_bf16_f32 v122, v24, v25
	v_cvt_pk_bf16_f32 v123, v26, v27
	v_cvt_pk_bf16_f32 v124, v20, v21
	v_cvt_pk_bf16_f32 v125, v22, v23
	ds_read_b128 v[20:23], v248 offset:208
	ds_read_b128 v[24:27], v248 offset:192
	v_lshlrev_b32_e32 v80, 16, v12
	v_and_b32_e32 v12, 0xffff0000, v12
	v_and_b32_e32 v78, 0xffff0000, v13
	v_lshlrev_b32_e32 v72, 16, v14
	v_and_b32_e32 v14, 0xffff0000, v14
	v_lshlrev_b32_e32 v84, 16, v7
	v_mov_b32_e32 v10, v14
	v_and_b32_e32 v86, 0xffff0000, v7
	v_mov_b32_e32 v5, v84
	v_mov_b32_e32 v7, v86
	s_waitcnt lgkmcnt(0)
	v_mul_f32_e32 v20, v91, v20
	v_mul_f32_e32 v24, v91, v24
	v_mul_f32_e32 v25, v91, v25
	v_mul_f32_e32 v21, v91, v21
	v_mul_f32_e32 v26, v91, v26
	v_mul_f32_e32 v22, v91, v22
	v_mul_f32_e32 v27, v91, v27
	v_mul_f32_e32 v23, v91, v23
	v_mul_f32_e32 v24, v24, v83
	v_mul_f32_e32 v20, v20, v87
	v_mul_f32_e32 v25, v25, v79
	v_mul_f32_e32 v21, v21, v85
	v_mul_f32_e32 v26, v26, v77
	v_mul_f32_e32 v22, v22, v81
	v_mul_f32_e32 v27, v27, v75
	v_mul_f32_e32 v23, v23, v73
	v_cvt_pk_bf16_f32 v126, v24, v25
	v_cvt_pk_bf16_f32 v127, v26, v27
	v_cvt_pk_bf16_f32 v128, v20, v21
	v_cvt_pk_bf16_f32 v129, v22, v23
	ds_read_b128 v[20:23], v248 offset:272
	ds_read_b128 v[24:27], v248 offset:256
	v_lshlrev_b32_e32 v73, 16, v18
	v_lshlrev_b32_e32 v81, 16, v16
	v_and_b32_e32 v79, 0xffff0000, v17
	v_lshlrev_b32_e32 v85, 16, v11
	v_and_b32_e32 v87, 0xffff0000, v11
	v_mov_b32_e32 v11, v94
	s_waitcnt lgkmcnt(0)
	v_mul_f32_e32 v20, v91, v20
	v_mul_f32_e32 v24, v91, v24
	v_mul_f32_e32 v25, v91, v25
	v_mul_f32_e32 v21, v91, v21
	v_mul_f32_e32 v26, v91, v26
	v_mul_f32_e32 v22, v91, v22
	v_mul_f32_e32 v27, v91, v27
	v_mul_f32_e32 v23, v91, v23
	v_mul_f32_e32 v24, v24, v68
	v_mul_f32_e32 v20, v20, v70
	v_mul_f32_e32 v25, v25, v64
	v_mul_f32_e32 v21, v21, v66
	v_mul_f32_e32 v26, v26, v60
	v_mul_f32_e32 v22, v22, v62
	v_mul_f32_e32 v27, v27, v58
	v_mul_f32_e32 v23, v23, v56
	v_cvt_pk_bf16_f32 v130, v24, v25
	v_cvt_pk_bf16_f32 v131, v26, v27
	v_cvt_pk_bf16_f32 v132, v20, v21
	v_cvt_pk_bf16_f32 v133, v22, v23
	ds_read_b128 v[20:23], v248 offset:336
	ds_read_b128 v[24:27], v248 offset:320
	v_lshl_or_b32 v64, v182, 3, v43
	v_lshlrev_b32_e32 v66, 16, v15
	v_and_b32_e32 v70, 0xffff0000, v15
	v_and_b32_e32 v15, 0xffff0000, v18
	v_lshlrev_b32_e32 v18, 16, v13
	v_and_b32_e32 v13, 0xffff0000, v16
	v_or_b32_e32 v16, 16, v64
	v_mov_b32_e32 v102, v13
	v_pk_mul_f32 v[102:103], v[102:103], v[102:103]
	v_mov_b32_e32 v6, v70
	s_waitcnt lgkmcnt(0)
	v_mul_f32_e32 v20, v91, v20
	v_mul_f32_e32 v24, v91, v24
	v_mul_f32_e32 v25, v91, v25
	v_mul_f32_e32 v21, v91, v21
	v_mul_f32_e32 v26, v91, v26
	v_mul_f32_e32 v22, v91, v22
	v_mul_f32_e32 v27, v91, v27
	v_mul_f32_e32 v23, v91, v23
	v_mul_f32_e32 v24, v24, v69
	v_mul_f32_e32 v20, v20, v71
	v_mul_f32_e32 v25, v25, v65
	v_mul_f32_e32 v21, v21, v67
	v_mul_f32_e32 v26, v26, v61
	v_mul_f32_e32 v22, v22, v63
	v_mul_f32_e32 v27, v27, v59
	v_mul_f32_e32 v23, v23, v57
	v_cvt_pk_bf16_f32 v134, v24, v25
	v_cvt_pk_bf16_f32 v135, v26, v27
	v_cvt_pk_bf16_f32 v136, v20, v21
	v_cvt_pk_bf16_f32 v137, v22, v23
	ds_read_b128 v[20:23], v248 offset:400
	ds_read_b128 v[24:27], v248 offset:384
	v_ashrrev_i32_e32 v65, 31, v64
	v_lshl_add_u64 v[60:61], v[64:65], 3, s[6:7]
	v_lshlrev_b32_e32 v67, 16, v19
	v_and_b32_e32 v71, 0xffff0000, v19
	v_lshlrev_b32_e32 v19, 16, v17
	v_ashrrev_i32_e32 v17, 31, v16
	v_lshl_add_u64 v[64:65], v[16:17], 3, s[6:7]
	v_mov_b32_e32 v16, v18
	v_mov_b32_e32 v17, v96
	s_waitcnt lgkmcnt(0)
	v_mul_f32_e32 v20, v91, v20
	v_mul_f32_e32 v24, v91, v24
	v_mul_f32_e32 v25, v91, v25
	v_mul_f32_e32 v21, v91, v21
	v_mul_f32_e32 v26, v91, v26
	v_mul_f32_e32 v22, v91, v22
	v_mul_f32_e32 v27, v91, v27
	v_mul_f32_e32 v23, v91, v23
	v_mul_f32_e32 v24, v24, v48
	v_mul_f32_e32 v20, v20, v54
	v_mul_f32_e32 v25, v25, v44
	v_mul_f32_e32 v21, v21, v52
	v_mul_f32_e32 v26, v26, v30
	v_mul_f32_e32 v22, v22, v50
	v_mul_f32_e32 v27, v27, v28
	v_mul_f32_e32 v23, v23, v46
	v_cvt_pk_bf16_f32 v138, v24, v25
	v_cvt_pk_bf16_f32 v139, v26, v27
	v_cvt_pk_bf16_f32 v140, v20, v21
	v_cvt_pk_bf16_f32 v141, v22, v23
	ds_read_b128 v[20:23], v248 offset:464
	ds_read_b128 v[24:27], v248 offset:448
	s_waitcnt lgkmcnt(0)
; __device__ __forceinline__ u32x4 pack8(const float* f) { u32x4 w; w.x = cvtpk(f[0], f[1]); w.y = cvtpk(f[2], f[3]); w.z = cvtpk(f[4], f[5]); w.w = cvtpk(f[6], f[7]); return w; }
; __device__ __forceinline__ bf16x8 pack8(const f32x4& a, const f32x4& b) { u32x4 w; w.x = cpk(a.x, a.y); w.y = cpk(a.z, a.w); w.z = cpk(b.x, b.y); w.w = cpk(b.z, b.w); return __builtin_bit_cast(bf16x8, w); }
; template <int VAR>
; __device__ __forceinline__ void attn_unit(const AUnit& u, LAS char* lds) {
;     ...
;         for (int d0 = 0; d0 < 8; ++d0) { float f[8]; unpack8(__builtin_bit_cast(u32x4, qr[d0]), f);
;             const f32x4 g0 = *(const f32x4*)(u.gqn + d0 * 16 + hi * 8), g1 = *(const f32x4*)(u.gqn + d0 * 16 + hi * 8 + 4);
; #pragma unroll
;             for (int e = 0; e < 4; ++e) { f[e] *= rn * g0[e]; f[4 + e] *= rn * g1[e]; }
;             qr[d0] = __builtin_bit_cast(bf16x8, pack8(f)); }
;         const int pos = u.pos0 + wq * 32 + r32;
; #pragma unroll
;         for (int a = 0; a < 2; ++a) { float x1[8], x2[8]; unpack8(__builtin_bit_cast(u32x4, qr[8 + a]), x1); unpack8(__builtin_bit_cast(u32x4, qr[10 + a]), x2);
;             const int i0 = a * 16 + hi * 8;
;             const f32x4 ga0 = *(const f32x4*)(u.gqr + i0), ga1 = *(const f32x4*)(u.gqr + i0 + 4), gb0 = *(const f32x4*)(u.gqr + 32 + i0), gb1 = *(const f32x4*)(u.gqr + 32 + i0 + 4);
;             float y1[8], y2[8];
; #pragma unroll
;             for (int e = 0; e < 8; ++e) { const float v1 = x1[e] * rr_ * (e < 4 ? ga0[e & 3] : ga1[e & 3]), v2 = x2[e] * rr_ * (e < 4 ? gb0[e & 3] : gb1[e & 3]);
;                 const float2 cs = u.tab[pos * 32 + i0 + e];
;                 y1[e] = (v1 * cs.x - v2 * cs.y) * QSCALE; y2[e] = (v2 * cs.x + v1 * cs.y) * QSCALE; }
;             qr[8 + a] = __builtin_bit_cast(bf16x8, pack8(y1)); qr[10 + a] = __builtin_bit_cast(bf16x8, pack8(y2)); }
	v_mul_f32_e32 v20, v91, v20
	v_mul_f32_e32 v24, v91, v24
	v_mul_f32_e32 v25, v91, v25
	v_mul_f32_e32 v21, v91, v21
	v_mul_f32_e32 v26, v91, v26
	v_mul_f32_e32 v22, v91, v22
	v_mul_f32_e32 v27, v91, v27
	v_mul_f32_e32 v23, v91, v23
	v_mul_f32_e32 v24, v24, v49
	v_mul_f32_e32 v20, v20, v55
	v_mul_f32_e32 v25, v25, v45
	v_mul_f32_e32 v21, v21, v53
	v_mul_f32_e32 v26, v26, v31
	v_mul_f32_e32 v22, v22, v51
	v_mul_f32_e32 v27, v27, v29
	v_mul_f32_e32 v23, v23, v47
	v_cvt_pk_bf16_f32 v142, v24, v25
	v_cvt_pk_bf16_f32 v143, v26, v27
	v_cvt_pk_bf16_f32 v144, v20, v21
	v_cvt_pk_bf16_f32 v145, v22, v23
	ds_read_b128 v[20:23], v248 offset:512
	ds_read_b128 v[24:27], v248 offset:528
	ds_read_b128 v[28:31], v248 offset:640
	ds_read_b128 v[44:47], v248 offset:656
	global_load_dwordx4 v[48:51], v[60:61], off offset:48
	global_load_dwordx4 v[52:55], v[60:61], off offset:32
	global_load_dwordx4 v[56:59], v[60:61], off offset:16
	s_nop 0
	global_load_dwordx4 v[60:63], v[60:61], off
	s_waitcnt vmcnt(0)
	s_waitcnt lgkmcnt(0)
	v_mov_b32_e32 v82, v20
	v_mov_b32_e32 v68, v26
	v_lshlrev_b32_e32 v20, 16, v4
	v_mov_b32_e32 v69, v46
	v_mov_b32_e32 v46, v27
	v_mov_b32_e32 v26, v12
	v_mov_b32_e32 v27, v100
	v_mov_b32_e32 v74, v24
	v_mov_b32_e32 v75, v44
	v_mov_b32_e32 v44, v25
	v_mov_b32_e32 v24, v80
	v_mov_b32_e32 v25, v20
	v_pk_mul_f32 v[26:27], v[26:27], v[26:27]
	v_mov_b32_e32 v83, v28
	v_mov_b32_e32 v28, v21
	v_lshlrev_b32_e32 v21, 16, v8
	v_pk_fma_f32 v[24:25], v[24:25], v[24:25], v[26:27]
	v_mov_b32_e32 v76, v22
	v_mov_b32_e32 v77, v30
	v_mov_b32_e32 v30, v23
	v_mov_b32_e32 v22, v78
	v_mov_b32_e32 v23, v98
	v_pk_fma_f32 v[16:17], v[16:17], v[16:17], v[24:25]
	v_mov_b32_e32 v26, v81
	v_mov_b32_e32 v27, v21
	v_mov_b32_e32 v8, v72
	v_pk_fma_f32 v[16:17], v[22:23], v[22:23], v[16:17]
	v_mov_b32_e32 v22, v19
	v_mov_b32_e32 v23, v97
	v_pk_fma_f32 v[26:27], v[26:27], v[26:27], v[102:103]
	v_pk_fma_f32 v[8:9], v[8:9], v[8:9], v[16:17]
	v_mov_b32_e32 v24, v79
	v_mov_b32_e32 v25, v99
	v_pk_fma_f32 v[22:23], v[22:23], v[22:23], v[26:27]
	v_mov_b32_e32 v4, v66
	v_pk_fma_f32 v[8:9], v[10:11], v[10:11], v[8:9]
	v_mov_b32_e32 v10, v73
	v_mov_b32_e32 v11, v93
	v_pk_fma_f32 v[22:23], v[24:25], v[24:25], v[22:23]
	v_pk_fma_f32 v[4:5], v[4:5], v[4:5], v[8:9]
	v_mov_b32_e32 v16, v15
	v_mov_b32_e32 v17, v95
	v_pk_fma_f32 v[10:11], v[10:11], v[10:11], v[22:23]
	v_pk_fma_f32 v[4:5], v[6:7], v[6:7], v[4:5]
	v_mov_b32_e32 v6, v67
	v_mov_b32_e32 v7, v85
	v_pk_fma_f32 v[10:11], v[16:17], v[16:17], v[10:11]
	v_mov_b32_e32 v8, v71
	v_mov_b32_e32 v9, v87
	v_pk_fma_f32 v[6:7], v[6:7], v[6:7], v[10:11]
	v_pk_add_f32 v[4:5], v[4:5], v[4:5] op_sel:[0,1] op_sel_hi:[1,0]
	v_pk_fma_f32 v[6:7], v[8:9], v[8:9], v[6:7]
	s_nop 0
	v_pk_add_f32 v[4:5], v[4:5], v[6:7]
	s_nop 0
	v_pk_add_f32 v[4:5], v[4:5], v[6:7] op_sel:[0,1] op_sel_hi:[1,0]
	s_nop 0
	v_mov_b32_e32 v5, v4
	s_nop 1
	v_permlane32_swap_b32_e32 v4, v5
	v_add_f32_e32 v4, v4, v5
	v_fmamk_f32 v4, v4, 0x3c800000, v1
	v_cmp_gt_f32_e32 vcc, s33, v4
	v_mul_f32_e32 v5, 0x4b800000, v4
	s_nop 0
	v_cndmask_b32_e32 v4, v4, v5, vcc
	v_rsq_f32_e32 v4, v4
	s_nop 0
	v_mul_f32_e32 v5, 0x45800000, v4
	v_cndmask_b32_e32 v102, v4, v5, vcc
	v_pk_mul_f32 v[4:5], v[102:103], v[80:81] op_sel_hi:[0,1]
	v_pk_mul_f32 v[4:5], v[4:5], v[82:83]
	v_pk_mul_f32 v[20:21], v[102:103], v[20:21] op_sel_hi:[0,1]
	v_pk_mul_f32 v[6:7], v[4:5], v[60:61]
	v_pk_mul_f32 v[4:5], v[4:5], v[60:61] op_sel:[1,0] op_sel_hi:[0,1]
	v_add_f32_e32 v4, v4, v5
	v_mul_f32_e32 v9, 0x3dd53b94, v4
	v_pk_mul_f32 v[4:5], v[102:103], v[12:13] op_sel_hi:[0,1]
	v_sub_f32_e32 v6, v6, v7
	v_pk_mul_f32 v[4:5], v[4:5], v[28:29]
	v_mul_f32_e32 v8, 0x3dd53b94, v6
	v_pk_mul_f32 v[6:7], v[4:5], v[62:63]
	v_pk_mul_f32 v[4:5], v[4:5], v[62:63] op_sel:[1,0] op_sel_hi:[0,1]
	v_add_f32_e32 v4, v4, v5
	v_mul_f32_e32 v11, 0x3dd53b94, v4
	v_pk_mul_f32 v[4:5], v[102:103], v[18:19] op_sel_hi:[0,1]
	v_sub_f32_e32 v6, v6, v7
	v_pk_mul_f32 v[4:5], v[4:5], v[76:77]
	v_mul_f32_e32 v10, 0x3dd53b94, v6
	v_pk_mul_f32 v[6:7], v[4:5], v[56:57]
	v_pk_mul_f32 v[4:5], v[4:5], v[56:57] op_sel:[1,0] op_sel_hi:[0,1]
	v_add_f32_e32 v4, v4, v5
	v_mul_f32_e32 v13, 0x3dd53b94, v4
	v_pk_mul_f32 v[4:5], v[102:103], v[78:79] op_sel_hi:[0,1]
	v_sub_f32_e32 v6, v6, v7
	v_pk_mul_f32 v[4:5], v[4:5], v[30:31]
	v_mul_f32_e32 v12, 0x3dd53b94, v6
	v_pk_mul_f32 v[6:7], v[4:5], v[58:59]
	v_pk_mul_f32 v[4:5], v[4:5], v[58:59] op_sel:[1,0] op_sel_hi:[0,1]
	v_add_f32_e32 v4, v4, v5
	v_mul_f32_e32 v17, 0x3dd53b94, v4
	v_pk_mul_f32 v[4:5], v[102:103], v[72:73] op_sel_hi:[0,1]
	v_sub_f32_e32 v6, v6, v7
	v_pk_mul_f32 v[4:5], v[4:5], v[74:75]
	v_mul_f32_e32 v16, 0x3dd53b94, v6
	v_pk_mul_f32 v[6:7], v[4:5], v[52:53]
	v_pk_mul_f32 v[4:5], v[4:5], v[52:53] op_sel:[1,0] op_sel_hi:[0,1]
	v_add_f32_e32 v4, v4, v5
	v_mul_f32_e32 v19, 0x3dd53b94, v4
	v_pk_mul_f32 v[4:5], v[102:103], v[14:15] op_sel_hi:[0,1]
	v_sub_f32_e32 v6, v6, v7
	v_pk_mul_f32 v[4:5], v[4:5], v[44:45]
	v_mul_f32_e32 v18, 0x3dd53b94, v6
	v_pk_mul_f32 v[6:7], v[4:5], v[54:55]
	v_pk_mul_f32 v[4:5], v[4:5], v[54:55] op_sel:[1,0] op_sel_hi:[0,1]
	v_add_f32_e32 v4, v4, v5
	v_mul_f32_e32 v15, 0x3dd53b94, v4
	v_pk_mul_f32 v[4:5], v[102:103], v[66:67] op_sel_hi:[0,1]
	v_sub_f32_e32 v6, v6, v7
	v_pk_mul_f32 v[4:5], v[4:5], v[68:69]
	v_mul_f32_e32 v14, 0x3dd53b94, v6
	v_pk_mul_f32 v[6:7], v[4:5], v[48:49]
	v_pk_mul_f32 v[4:5], v[4:5], v[48:49] op_sel:[1,0] op_sel_hi:[0,1]
	v_add_f32_e32 v4, v4, v5
	v_mul_f32_e32 v23, 0x3dd53b94, v4
	v_pk_mul_f32 v[4:5], v[102:103], v[70:71] op_sel_hi:[0,1]
	v_sub_f32_e32 v6, v6, v7
	v_pk_mul_f32 v[4:5], v[4:5], v[46:47]
	v_mul_f32_e32 v22, 0x3dd53b94, v6
	v_pk_mul_f32 v[6:7], v[4:5], v[50:51]
	v_pk_mul_f32 v[4:5], v[4:5], v[50:51] op_sel:[1,0] op_sel_hi:[0,1]
	v_sub_f32_e32 v6, v6, v7
	v_add_f32_e32 v4, v4, v5
	v_mul_f32_e32 v6, 0x3dd53b94, v6
	v_mul_f32_e32 v4, 0x3dd53b94, v4
	v_cvt_pk_bf16_f32 v146, v8, v10
	v_cvt_pk_bf16_f32 v147, v12, v16
	v_cvt_pk_bf16_f32 v148, v18, v14
	v_cvt_pk_bf16_f32 v149, v22, v6
	v_cvt_pk_bf16_f32 v150, v9, v11
	v_cvt_pk_bf16_f32 v151, v13, v17
	v_cvt_pk_bf16_f32 v152, v19, v15
	v_cvt_pk_bf16_f32 v153, v23, v4
	ds_read_b128 v[4:7], v248 offset:592
	ds_read_b128 v[8:11], v248 offset:576
	ds_read_b128 v[12:15], v248 offset:720
	ds_read_b128 v[16:19], v248 offset:704
	s_waitcnt lgkmcnt(0)
; #define LAS __attribute__((address_space(3)))
; __device__ __forceinline__ u32x4 pack8(const float* f) { u32x4 w; w.x = cvtpk(f[0], f[1]); w.y = cvtpk(f[2], f[3]); w.z = cvtpk(f[4], f[5]); w.w = cvtpk(f[6], f[7]); return w; }
; __device__ __forceinline__ int v_rd_base(int lane) { return ((lane & 3) << 3) | (((lane >> 2) & 3) << 6) | (((lane >> 4) & 1) << 5) | (((lane >> 5) & 1) << 8); }
; #define AWAITV() asm volatile("s_waitcnt vmcnt(0)" ::: "memory")
; __device__ __forceinline__ bf16x8 pack8(const f32x4& a, const f32x4& b) { u32x4 w; w.x = cpk(a.x, a.y); w.y = cpk(a.z, a.w); w.z = cpk(b.x, b.y); w.w = cpk(b.z, b.w); return __builtin_bit_cast(bf16x8, w); }
; template <int VAR>
; __device__ __forceinline__ void attn_unit(const AUnit& u, LAS char* lds) {
;     ...
; #pragma unroll
;         for (int a = 0; a < 2; ++a) { float x1[8], x2[8]; unpack8(__builtin_bit_cast(u32x4, qr[8 + a]), x1); unpack8(__builtin_bit_cast(u32x4, qr[10 + a]), x2);
;             const int i0 = a * 16 + hi * 8;
;             const f32x4 ga0 = *(const f32x4*)(u.gqr + i0), ga1 = *(const f32x4*)(u.gqr + i0 + 4), gb0 = *(const f32x4*)(u.gqr + 32 + i0), gb1 = *(const f32x4*)(u.gqr + 32 + i0 + 4);
;             float y1[8], y2[8];
; #pragma unroll
;             for (int e = 0; e < 8; ++e) { const float v1 = x1[e] * rr_ * (e < 4 ? ga0[e & 3] : ga1[e & 3]), v2 = x2[e] * rr_ * (e < 4 ? gb0[e & 3] : gb1[e & 3]);
;                 const float2 cs = u.tab[pos * 32 + i0 + e];
;                 y1[e] = (v1 * cs.x - v2 * cs.y) * QSCALE; y2[e] = (v2 * cs.x + v1 * cs.y) * QSCALE; }
;             qr[8 + a] = __builtin_bit_cast(bf16x8, pack8(y1)); qr[10 + a] = __builtin_bit_cast(bf16x8, pack8(y2)); }
;     }
;     float m_reg = -1e30f, l_reg = 0.f; f32x16 o[4]; o[0] = f32x16{}; o[1] = f32x16{}; o[2] = f32x16{}; o[3] = f32x16{};
;     LAS float* wsf = (LAS float*)(lds + OFF_WS) + wid * 64; LAS float* li_l = wsf; LAS float* al_l = wsf + 32;
;     const int vb0 = (int)(unsigned)(uintptr_t)lds + v_rd_base(lane);
;     AWAITV();
;     __syncthreads();
	v_mov_b32_e32 v22, v8
	v_mov_b32_e32 v23, v16
	v_pk_mul_f32 v[48:49], v[20:21], v[22:23]
	global_load_dwordx4 v[20:23], v[64:65], off offset:48
	global_load_dwordx4 v[24:27], v[64:65], off offset:32
	global_load_dwordx4 v[28:31], v[64:65], off offset:16
	global_load_dwordx4 v[44:47], v[64:65], off
	v_mov_b32_e32 v16, v9
	s_waitcnt vmcnt(0)
	v_pk_mul_f32 v[50:51], v[48:49], v[44:45]
	s_nop 0
	v_sub_f32_e32 v8, v50, v51
	v_pk_mul_f32 v[44:45], v[48:49], v[44:45] op_sel:[1,0] op_sel_hi:[0,1]
	v_mul_f32_e32 v43, 0x3dd53b94, v8
	v_add_f32_e32 v8, v44, v45
	v_pk_mul_f32 v[44:45], v[102:103], v[100:101] op_sel_hi:[0,1]
	v_mul_f32_e32 v48, 0x3dd53b94, v8
	v_pk_mul_f32 v[8:9], v[44:45], v[16:17]
	s_nop 0
	v_pk_mul_f32 v[16:17], v[8:9], v[46:47]
	v_pk_mul_f32 v[8:9], v[8:9], v[46:47] op_sel:[1,0] op_sel_hi:[0,1]
	v_sub_f32_e32 v16, v16, v17
	v_add_f32_e32 v8, v8, v9
	v_mul_f32_e32 v44, 0x3dd53b94, v16
	v_mul_f32_e32 v45, 0x3dd53b94, v8
	v_pk_mul_f32 v[8:9], v[102:103], v[96:97] op_sel_hi:[0,1]
	v_mov_b32_e32 v16, v10
	v_mov_b32_e32 v17, v18
	v_pk_mul_f32 v[8:9], v[8:9], v[16:17]
	v_mov_b32_e32 v18, v11
	v_pk_mul_f32 v[16:17], v[8:9], v[28:29]
	v_pk_mul_f32 v[8:9], v[8:9], v[28:29] op_sel:[1,0] op_sel_hi:[0,1]
	v_add_f32_e32 v8, v8, v9
	v_sub_f32_e32 v10, v16, v17
	v_mul_f32_e32 v17, 0x3dd53b94, v8
	v_pk_mul_f32 v[8:9], v[102:103], v[98:99] op_sel_hi:[0,1]
	v_pk_mul_f32 v[8:9], v[8:9], v[18:19]
	v_mul_f32_e32 v16, 0x3dd53b94, v10
	v_pk_mul_f32 v[10:11], v[8:9], v[30:31]
	v_pk_mul_f32 v[8:9], v[8:9], v[30:31] op_sel:[1,0] op_sel_hi:[0,1]
	v_sub_f32_e32 v10, v10, v11
	v_add_f32_e32 v8, v8, v9
	v_mul_f32_e32 v18, 0x3dd53b94, v10
	v_mul_f32_e32 v19, 0x3dd53b94, v8
	v_pk_mul_f32 v[8:9], v[102:103], v[92:93] op_sel_hi:[0,1]
	v_mov_b32_e32 v10, v4
	v_mov_b32_e32 v11, v12
	v_pk_mul_f32 v[8:9], v[8:9], v[10:11]
	v_mov_b32_e32 v12, v5
	v_pk_mul_f32 v[10:11], v[8:9], v[24:25]
	v_pk_mul_f32 v[8:9], v[8:9], v[24:25] op_sel:[1,0] op_sel_hi:[0,1]
	v_sub_f32_e32 v4, v10, v11
	v_mul_f32_e32 v10, 0x3dd53b94, v4
	v_add_f32_e32 v4, v8, v9
	v_pk_mul_f32 v[8:9], v[102:103], v[94:95] op_sel_hi:[0,1]
	v_mul_f32_e32 v11, 0x3dd53b94, v4
	v_pk_mul_f32 v[4:5], v[8:9], v[12:13]
	v_cvt_pk_bf16_f32 v154, v43, v44
	v_cvt_pk_bf16_f32 v155, v16, v18
	v_mov_b32_e32 v16, v3
	v_pk_mul_f32 v[8:9], v[4:5], v[26:27]
	v_pk_mul_f32 v[4:5], v[4:5], v[26:27] op_sel:[1,0] op_sel_hi:[0,1]
	v_sub_f32_e32 v8, v8, v9
	v_add_f32_e32 v4, v4, v5
	v_mul_f32_e32 v12, 0x3dd53b94, v8
	v_mul_f32_e32 v13, 0x3dd53b94, v4
	v_pk_mul_f32 v[4:5], v[102:103], v[84:85] op_sel_hi:[0,1]
	v_mov_b32_e32 v8, v6
	v_mov_b32_e32 v9, v14
	v_pk_mul_f32 v[4:5], v[4:5], v[8:9]
	v_mov_b32_e32 v14, v7
	v_pk_mul_f32 v[8:9], v[4:5], v[20:21]
	v_pk_mul_f32 v[4:5], v[4:5], v[20:21] op_sel:[1,0] op_sel_hi:[0,1]
	v_add_f32_e32 v4, v4, v5
	v_sub_f32_e32 v6, v8, v9
	v_mul_f32_e32 v9, 0x3dd53b94, v4
	v_pk_mul_f32 v[4:5], v[102:103], v[86:87] op_sel_hi:[0,1]
	v_pk_mul_f32 v[4:5], v[4:5], v[14:15]
	v_mul_f32_e32 v8, 0x3dd53b94, v6
	v_pk_mul_f32 v[6:7], v[4:5], v[22:23]
	v_pk_mul_f32 v[4:5], v[4:5], v[22:23] op_sel:[1,0] op_sel_hi:[0,1]
	v_sub_f32_e32 v6, v6, v7
	v_add_f32_e32 v4, v4, v5
	v_mul_f32_e32 v6, 0x3dd53b94, v6
	v_mul_f32_e32 v4, 0x3dd53b94, v4
	v_lshlrev_b32_e32 v5, 4, v181
	v_cvt_pk_bf16_f32 v156, v10, v12
	v_cvt_pk_bf16_f32 v157, v8, v6
	v_cvt_pk_bf16_f32 v158, v48, v45
	v_cvt_pk_bf16_f32 v159, v17, v19
	v_cvt_pk_bf16_f32 v160, v11, v13
	v_cvt_pk_bf16_f32 v161, v9, v4
	v_lshlrev_b32_e32 v4, 3, v88
	v_and_b32_e32 v6, 0xc0, v5
	v_lshlrev_b32_e32 v7, 1, v181
	v_and_or_b32 v6, v4, 24, v6
	v_and_b32_e32 v7, 32, v7
	v_and_b32_e32 v4, 0x100, v4
	v_or3_b32 v4, v6, v7, v4
	v_add_u32_e32 v163, 0, v4
	v_and_b32_e32 v4, 0xf0, v5
	v_bitop3_b32 v185, v162, v4, 32 bitop3:0x36
	v_bitop3_b32 v186, v162, v4, 64 bitop3:0x36
	v_bitop3_b32 v187, v162, v4, s24 bitop3:0x36
	v_bitop3_b32 v207, v162, v4, s23 bitop3:0x36
	v_bitop3_b32 v208, v162, v4, s25 bitop3:0x36
	v_bitop3_b32 v209, v162, v4, s14 bitop3:0x36
	v_bitop3_b32 v210, v162, v4, s15 bitop3:0x36
	v_lshlrev_b32_e32 v4, 7, v180
	v_sub_u32_e32 v211, v183, v4
	v_add_u32_e32 v224, s10, v4
	v_bitop3_b32 v4, v32, 15, v181 bitop3:0x48
	v_lshl_or_b32 v34, v4, 4, v34
	v_bitop3_b32 v4, v33, 7, v181 bitop3:0x48
	s_waitcnt vmcnt(0)
	v_bitop3_b32 v184, v162, v5, s20 bitop3:0x78
	v_and_b32_e32 v5, 0x70, v89
	v_lshl_or_b32 v38, v4, 4, v38
	v_mov_b32_e32 v17, v3
	v_bitop3_b32 v213, v162, v5, 32 bitop3:0x36
	v_bitop3_b32 v214, v162, v5, 64 bitop3:0x36
	v_bitop3_b32 v215, v162, v5, s24 bitop3:0x36
	v_lshl_add_u64 v[174:175], s[50:51], 0, v[34:35]
	v_lshl_add_u64 v[176:177], s[52:53], 0, v[38:39]
	v_mov_b32_e32 v4, v3
	v_mov_b32_e32 v5, v3
	v_mov_b32_e32 v6, v3
	v_mov_b32_e32 v7, v3
	v_mov_b32_e32 v8, v3
	v_mov_b32_e32 v9, v3
	v_mov_b32_e32 v10, v3
	v_mov_b32_e32 v11, v3
	v_mov_b32_e32 v12, v3
	v_mov_b32_e32 v13, v3
	v_mov_b32_e32 v14, v3
	v_mov_b32_e32 v15, v3
	v_mov_b64_e32 v[32:33], v[16:17]
	v_mov_b64_e32 v[48:49], v[16:17]
	v_mov_b64_e32 v[64:65], v[16:17]
	v_mov_b64_e32 v[80:81], v[16:17]
	v_add3_u32 v216, v183, v184, s22
	v_add3_u32 v217, v183, v185, s22
	v_add3_u32 v218, v183, v186, s22
	v_add3_u32 v219, v183, v187, s22
	v_add3_u32 v220, v183, v207, s22
	v_add3_u32 v221, v183, v208, s22
	v_add3_u32 v222, v183, v209, s22
	v_add3_u32 v223, v183, v210, s22
	v_mov_b64_e32 v[30:31], v[14:15]
	v_mov_b64_e32 v[28:29], v[12:13]
	v_mov_b64_e32 v[26:27], v[10:11]
	v_mov_b64_e32 v[24:25], v[8:9]
	v_mov_b64_e32 v[22:23], v[6:7]
	v_mov_b64_e32 v[20:21], v[4:5]
	v_mov_b64_e32 v[18:19], v[2:3]
	v_mov_b64_e32 v[46:47], v[14:15]
	v_mov_b64_e32 v[44:45], v[12:13]
	v_mov_b64_e32 v[42:43], v[10:11]
	v_mov_b64_e32 v[40:41], v[8:9]
	v_mov_b64_e32 v[38:39], v[6:7]
	v_mov_b64_e32 v[36:37], v[4:5]
	v_mov_b64_e32 v[34:35], v[2:3]
	v_mov_b64_e32 v[62:63], v[14:15]
	v_mov_b64_e32 v[60:61], v[12:13]
	v_mov_b64_e32 v[58:59], v[10:11]
	v_mov_b64_e32 v[56:57], v[8:9]
	v_mov_b64_e32 v[54:55], v[6:7]
	v_mov_b64_e32 v[52:53], v[4:5]
	v_mov_b64_e32 v[50:51], v[2:3]
	v_mov_b64_e32 v[78:79], v[14:15]
	v_mov_b64_e32 v[76:77], v[12:13]
	v_mov_b64_e32 v[74:75], v[10:11]
	v_mov_b64_e32 v[72:73], v[8:9]
	v_mov_b64_e32 v[70:71], v[6:7]
	v_mov_b64_e32 v[68:69], v[4:5]
	v_mov_b64_e32 v[66:67], v[2:3]
	s_waitcnt lgkmcnt(0)
	s_barrier
	v_readfirstlane_b32 s93, v181
	s_nop 3
	s_lshr_b32 s93, s93, 8
	s_cmp_eq_u32 s93, 0
	s_cbranch_scc0 .Latt_startB

; #define LAS __attribute__((address_space(3)))
; template <int VAR>
; __device__ __forceinline__ void attn_unit(const AUnit& u, LAS char* lds) {
;     ...
;     const bool wact = wid < u.nwav;
;     const int jmax = u.jbase + (wid >> 1);
;     const bf16_t* gk0; const bf16_t* gk1; const bf16_t* gkr; const bf16_t* gv0; const bf16_t* gv1;
;     {
;         const int rk0 = (2 * wid) * 4 + (lane >> 4), rk1 = rk0 + 4, ph = lane & 15;
;         gk0 = u.Kn + (size_t)rk0 * 128 + ((ph ^ (rk0 & 15)) * 8);
;         gk1 = u.Kn + (size_t)rk1 * 128 + ((ph ^ (rk1 & 15)) * 8);
;         const int rr0 = wid * 8 + (lane >> 3), pr = lane & 7;
;         gkr = u.Kr + (size_t)rr0 * ROPE + ((pr ^ ((rr0 >> 1) & 7)) * 8);
; #pragma unroll
;         for (int i = 0; i < 2; ++i) {
;             const int st = (2 * wid + i) * 2 + (lane >> 5), o16 = lane & 31, kk = (st >> 2) * 8 + (o16 >> 2), c = (st & 3) * 32 + (o16 & 3) * 8;
;             const int key = (kk & ~0xC) | ((kk & 4) << 1) | ((kk & 8) >> 1);
;             const bf16_t* p = u.V + (size_t)key * 128 + c;
;             if (i == 0) gv0 = p; else gv1 = p;
;         }
;     }
;     ...
;     ADMA(0, 0);
;     bf16x8 qr[12];
;     {
;         const int wq = wact ? wid : 0;
;         const bf16_t* qp = u.Q + (size_t)(wq * 32 + r32) * QW + hi * 8;
; #pragma unroll
;         for (int d0 = 0; d0 < 12; ++d0) qr[d0] = *(const bf16x8*)(qp + d0 * 16);
; __global__ void __launch_bounds__(NWAVES * 64, 2) mk_fwd(Args args) {
;     ...
;                 {
;                     const int sb = v >> 4, sh = v & 15;
;                     const size_t m0 = (size_t)MP + (size_t)sb * DS, k0 = (size_t)MP + (size_t)sb * SKEYS;
;                     att::AUnit u{Qb + m0 * QW + sh * 192, Kn + ((size_t)sh * KROWS + k0) * 128, Vb + ((size_t)sh * KROWS + k0) * 128, Krb + k0 * ROPE, hmix + m0 * DM + RW + sh * 128, 33, 1, 32, 1, PAST, gqn, gqr, tab};
;                     att::attn_unit<0>(u, (LAS char*)lds);
.LBB0_1100:
	s_ashr_i32 s4, s74, 4
	s_ashr_i32 s5, s4, 31
	s_and_b32 s58, s63, 15
	s_and_b32 s52, s74, 15
	s_lshl_b64 s[2:3], s[4:5], 5
	s_add_u32 s40, s2, 0x4000
	s_addc_u32 s41, s3, 0
	s_lshl_b64 s[2:3], s[4:5], 11
	s_add_u32 s46, s40, s2
	s_addc_u32 s47, s41, s3
	s_mul_i32 s2, s41, 0x1800
	s_mul_hi_u32 s3, s40, 0x1800
	s_add_i32 s3, s3, s2
	s_mul_i32 s2, s40, 0x1800
	s_add_u32 s2, s70, s2
	s_addc_u32 s3, s71, s3
	s_mul_i32 s5, s52, 0x180
	s_add_u32 s2, s2, s5
	s_addc_u32 s3, s3, 0
	s_mul_i32 s5, s52, 0xc200
	s_add_u32 s42, s46, s5
	s_addc_u32 s43, s47, 0
	s_lshl_b64 s[42:43], s[42:43], 8
	s_add_u32 s48, s66, s42
	s_addc_u32 s49, s67, s43
	s_add_u32 s42, s68, s42
	s_addc_u32 s43, s69, s43
	s_lshl_b64 s[46:47], s[46:47], 7
	v_mov_b32_e32 v181, v0
	s_add_u32 s50, s72, s46
	s_addc_u32 s51, s73, s47
	v_readfirstlane_b32 s5, v181
	s_ashr_i32 s46, s5, 6
	s_lshl_b32 s47, s46, 3
	s_waitcnt lgkmcnt(0)
	v_bfe_u32 v2, v181, 4, 2
	v_or_b32_e32 v4, s47, v2
	v_and_b32_e32 v2, 15, v181
	v_ashrrev_i32_e32 v5, 31, v4
	v_bitop3_b32 v10, v4, v2, 11 bitop3:0x6c
	v_bfe_u32 v2, v181, 3, 3
	v_or_b32_e32 v32, 4, v4
	v_lshlrev_b64 v[38:39], 8, v[4:5]
	v_bitop3_b32 v12, v4, v181, 4 bitop3:0x36
	v_or_b32_e32 v4, s47, v2
	v_ashrrev_i32_e32 v33, 31, v32
	v_ashrrev_i32_e32 v5, 31, v4
	v_bfe_u32 v2, v181, 2, 3
	v_lshlrev_b64 v[34:35], 8, v[32:33]
	v_lshlrev_b64 v[36:37], 7, v[4:5]
	v_lshrrev_b32_e32 v33, 1, v4
	v_bitop3_b32 v2, s47, -13, v2 bitop3:0xc8
	v_lshrrev_b32_e32 v4, 1, v181
	s_lshl_b32 s47, s46, 2
	v_and_b32_e32 v4, 8, v4
	s_and_b32 s47, s47, 4
	v_or3_b32 v4, v2, v4, s47
	v_ashrrev_i32_e32 v5, 31, v4
	v_lshlrev_b64 v[40:41], 8, v[4:5]
	v_lshl_add_u64 v[4:5], s[42:43], 0, v[40:41]
	s_lshl_b32 s42, s46, 11
	s_add_i32 s43, s42, 0
	s_lshl_b32 s42, s46, 10
	s_add_i32 s55, s42, 0
	s_ashr_i32 s19, s5, 7
	v_xor_b32_e32 v14, v33, v181
	s_add_i32 s53, s43, 0x8000
	s_add_i32 s54, s43, 0x8400
	s_add_i32 s56, s55, 0xc000
	s_add_i32 s57, s43, 0x400
	s_lshl_b32 s42, s46, 5
	v_lshl_add_u64 v[8:9], s[48:49], 0, v[38:39]
	v_lshlrev_b32_e32 v42, 4, v10
	v_mov_b32_e32 v43, v3
	v_lshlrev_b32_e32 v12, 4, v12
	s_waitcnt vmcnt(2)
	v_and_b32_e32 v90, 32, v181
	v_lshrrev_b32_e32 v248, 6, v181
	v_lshl_add_u32 v248, v248, 10, v90
	v_add_u32_e32 v248, 0x15000, v248
	s_waitcnt vmcnt(1)
	v_lshlrev_b32_e32 v89, 3, v181
	s_cmp_lt_i32 s46, 1
	v_lshl_add_u64 v[8:9], v[8:9], 0, v[42:43]
	v_lshl_add_u64 v[10:11], s[48:49], 0, v[34:35]
	v_and_b32_e32 v12, 0xf0, v12
	v_mov_b32_e32 v13, v3
	v_lshlrev_b32_e32 v14, 4, v14
	s_mov_b32 m0, s53
	v_and_or_b32 v6, v89, 24, v90
	s_cselect_b64 s[46:47], -1, 0
	v_lshl_add_u64 v[10:11], v[10:11], 0, v[12:13]
	v_lshl_add_u64 v[12:13], s[50:51], 0, v[36:37]
	v_and_b32_e32 v14, 0x70, v14
	v_mov_b32_e32 v15, v3
	global_load_lds_dwordx4 v[8:9], off
	s_mov_b32 m0, s54
	v_lshlrev_b32_e32 v2, 1, v6
	v_lshl_add_u64 v[12:13], v[12:13], 0, v[14:15]
	global_load_lds_dwordx4 v[10:11], off
	s_mov_b32 m0, s56
	s_and_b64 s[48:49], s[46:47], exec
	v_and_b32_e32 v180, 31, v181
	v_lshl_add_u64 v[4:5], v[4:5], 0, v[2:3]
	global_load_lds_dwordx4 v[12:13], off
	s_mov_b32 m0, s43
	s_cselect_b32 s48, s42, 0
	v_lshl_add_u64 v[6:7], v[4:5], 0, s[28:29]
	v_bfe_u32 v182, v181, 5, 1
	global_load_lds_dwordx4 v[4:5], off
	v_or_b32_e32 v43, s48, v180
	v_mov_b64_e32 v[4:5], s[2:3]
	s_mov_b32 m0, s57
	v_mad_i64_i32 v[4:5], s[2:3], v43, s45, v[4:5]
	v_lshlrev_b32_e32 v162, 4, v182
	v_mov_b32_e32 v163, v3
	global_load_lds_dwordx4 v[6:7], off
	v_lshl_add_u64 v[8:9], v[4:5], 0, v[162:163]
	global_load_dwordx4 v[28:31], v[8:9], off
	global_load_dwordx4 v[24:27], v[8:9], off offset:32
	global_load_dwordx4 v[20:23], v[8:9], off offset:64
	global_load_dwordx4 v[44:47], v[8:9], off offset:96
	global_load_dwordx4 v[48:51], v[8:9], off offset:128
	global_load_dwordx4 v[52:55], v[8:9], off offset:160
	global_load_dwordx4 v[110:113], v[8:9], off offset:192
	global_load_dwordx4 v[114:117], v[8:9], off offset:224
	global_load_dwordx4 v[12:15], v[8:9], off offset:256
	global_load_dwordx4 v[4:7], v[8:9], off offset:288
	global_load_dwordx4 v[16:19], v[8:9], off offset:320
	s_nop 0
	global_load_dwordx4 v[8:11], v[8:9], off offset:352
	v_lshlrev_b32_e32 v91, 3, v182
	v_lshl_or_b32 v43, v43, 5, v91
	s_waitcnt vmcnt(0)
	v_and_b32_e32 v88, 63, v181
	s_and_b32 s2, s5, 0x3fffffc0
	s_lshl_b32 s2, s2, 2
	s_add_i32 s50, s19, 32
	s_add_i32 s19, s2, 0
	s_mul_i32 s58, s58, 0xc20000
	s_add_i32 s19, s19, 0x14000
	s_mul_hi_i32 s5, s4, 0x82000
	v_lshl_add_u32 v183, v180, 8, 0
	v_bitop3_b32 v212, v162, v89, s21 bitop3:0x78
	v_cmp_gt_u32_e64 s[2:3], 32, v88
	v_lshl_add_u32 v206, v180, 2, s19
	v_mov_b32_e32 v225, 0
	v_mov_b32_e32 v226, 0xf149f2ca
	v_and_b32_e32 v105, 0xffff0000, v28
	v_and_b32_e32 v97, 0xffff0000, v24
	v_lshlrev_b32_e32 v107, 16, v28
	v_mul_f32_e32 v28, v105, v105
	v_lshlrev_b32_e32 v101, 16, v24
	v_mul_f32_e32 v24, v97, v97
	v_and_b32_e32 v79, 0xffff0000, v44
	v_and_b32_e32 v78, 0xffff0000, v20
	v_lshlrev_b32_e32 v102, 16, v29
	v_fmac_f32_e32 v28, v107, v107
	v_lshlrev_b32_e32 v95, 16, v25
	v_fmac_f32_e32 v24, v101, v101
	v_lshlrev_b32_e32 v83, 16, v44
	v_lshlrev_b32_e32 v82, 16, v20
	v_lshlrev_b32_e32 v76, 16, v21
	v_and_b32_e32 v74, 0xffff0000, v21
	v_pk_mul_f32 v[20:21], v[78:79], v[78:79]
	v_and_b32_e32 v98, 0xffff0000, v29
	v_fmac_f32_e32 v28, v102, v102
	v_and_b32_e32 v93, 0xffff0000, v25
	v_fmac_f32_e32 v24, v95, v95
	v_lshlrev_b32_e32 v77, 16, v45
	v_pk_fma_f32 v[20:21], v[82:83], v[82:83], v[20:21]
	v_lshlrev_b32_e32 v108, 16, v30
	v_fmac_f32_e32 v28, v98, v98
	v_lshlrev_b32_e32 v103, 16, v26
	v_fmac_f32_e32 v24, v93, v93
	v_and_b32_e32 v75, 0xffff0000, v45
	v_pk_fma_f32 v[20:21], v[76:77], v[76:77], v[20:21]
; __device__ __forceinline__ u32x4 pack8(const float* f) { u32x4 w; w.x = cvtpk(f[0], f[1]); w.y = cvtpk(f[2], f[3]); w.z = cvtpk(f[4], f[5]); w.w = cvtpk(f[6], f[7]); return w; }
; __device__ __forceinline__ bf16x8 pack8(const f32x4& a, const f32x4& b) { u32x4 w; w.x = cpk(a.x, a.y); w.y = cpk(a.z, a.w); w.z = cpk(b.x, b.y); w.w = cpk(b.z, b.w); return __builtin_bit_cast(bf16x8, w); }
; template <int VAR>
; __device__ __forceinline__ void attn_unit(const AUnit& u, LAS char* lds) {
;     ...
;         float ssn = 0.f, ssr = 0.f;
; #pragma unroll
;         for (int d0 = 0; d0 < 12; ++d0) { float f[8]; unpack8(__builtin_bit_cast(u32x4, qr[d0]), f); float a = 0.f;
; #pragma unroll
;             for (int e = 0; e < 8; ++e) a += f[e] * f[e];
;             if (d0 < 8) ssn += a; else ssr += a; }
;         { auto rr = __builtin_amdgcn_permlane32_swap(__float_as_uint(ssn), __float_as_uint(ssn), false, false); ssn = __uint_as_float(rr[0]) + __uint_as_float(rr[1]); }
;         { auto rr = __builtin_amdgcn_permlane32_swap(__float_as_uint(ssr), __float_as_uint(ssr), false, false); ssr = __uint_as_float(rr[0]) + __uint_as_float(rr[1]); }
;         const float rn = rsqrtf(ssn * (1.f / 128) + NORM_EPS) * QSCALE, rr_ = rsqrtf(ssr * (1.f / ROPE) + NORM_EPS);
; #pragma unroll
;         for (int d0 = 0; d0 < 8; ++d0) { float f[8]; unpack8(__builtin_bit_cast(u32x4, qr[d0]), f);
;             const f32x4 g0 = *(const f32x4*)(u.gqn + d0 * 16 + hi * 8), g1 = *(const f32x4*)(u.gqn + d0 * 16 + hi * 8 + 4);
; #pragma unroll
;             for (int e = 0; e < 4; ++e) { f[e] *= rn * g0[e]; f[4 + e] *= rn * g1[e]; }
;             qr[d0] = __builtin_bit_cast(bf16x8, pack8(f)); }
	v_and_b32_e32 v106, 0xffff0000, v30
	v_fmac_f32_e32 v28, v108, v108
	v_and_b32_e32 v99, 0xffff0000, v26
	v_fmac_f32_e32 v24, v103, v103
	v_lshlrev_b32_e32 v87, 16, v46
	v_lshlrev_b32_e32 v86, 16, v22
	v_pk_fma_f32 v[20:21], v[74:75], v[74:75], v[20:21]
	v_lshlrev_b32_e32 v104, 16, v31
	v_fmac_f32_e32 v28, v106, v106
	v_lshlrev_b32_e32 v96, 16, v27
	v_fmac_f32_e32 v24, v99, v99
	v_and_b32_e32 v85, 0xffff0000, v46
	v_and_b32_e32 v84, 0xffff0000, v22
	v_pk_fma_f32 v[20:21], v[86:87], v[86:87], v[20:21]
	v_and_b32_e32 v100, 0xffff0000, v31
	v_fmac_f32_e32 v28, v104, v104
	v_and_b32_e32 v94, 0xffff0000, v27
	v_fmac_f32_e32 v24, v96, v96
	v_lshlrev_b32_e32 v81, 16, v47
	v_lshlrev_b32_e32 v80, 16, v23
	v_pk_fma_f32 v[20:21], v[84:85], v[84:85], v[20:21]
	v_fmac_f32_e32 v28, v100, v100
	v_fmac_f32_e32 v24, v94, v94
	v_and_b32_e32 v73, 0xffff0000, v47
	v_and_b32_e32 v72, 0xffff0000, v23
	v_pk_fma_f32 v[20:21], v[80:81], v[80:81], v[20:21]
	v_add_f32_e32 v24, v28, v24
	v_pk_fma_f32 v[20:21], v[72:73], v[72:73], v[20:21]
	v_and_b32_e32 v65, 0xffff0000, v52
	v_add_f32_e32 v20, v24, v20
	v_and_b32_e32 v64, 0xffff0000, v48
	v_add_f32_e32 v22, v20, v21
	v_lshlrev_b32_e32 v69, 16, v52
	v_lshlrev_b32_e32 v68, 16, v48
	v_pk_mul_f32 v[20:21], v[64:65], v[64:65]
	v_lshlrev_b32_e32 v61, 16, v53
	v_lshlrev_b32_e32 v60, 16, v49
	v_pk_fma_f32 v[20:21], v[68:69], v[68:69], v[20:21]
	v_and_b32_e32 v59, 0xffff0000, v53
	v_and_b32_e32 v58, 0xffff0000, v49
	v_pk_fma_f32 v[20:21], v[60:61], v[60:61], v[20:21]
	v_lshlrev_b32_e32 v71, 16, v54
	v_lshlrev_b32_e32 v70, 16, v50
	v_pk_fma_f32 v[20:21], v[58:59], v[58:59], v[20:21]
	v_and_b32_e32 v67, 0xffff0000, v54
	v_and_b32_e32 v66, 0xffff0000, v50
	v_pk_fma_f32 v[20:21], v[70:71], v[70:71], v[20:21]
	v_lshlrev_b32_e32 v63, 16, v55
	v_lshlrev_b32_e32 v62, 16, v51
	v_pk_fma_f32 v[20:21], v[66:67], v[66:67], v[20:21]
	v_and_b32_e32 v57, 0xffff0000, v55
	v_and_b32_e32 v56, 0xffff0000, v51
	v_pk_fma_f32 v[20:21], v[62:63], v[62:63], v[20:21]
	v_and_b32_e32 v45, 0xffff0000, v114
	v_pk_fma_f32 v[20:21], v[56:57], v[56:57], v[20:21]
	v_and_b32_e32 v44, 0xffff0000, v110
	v_add_f32_e32 v20, v22, v20
	v_add_f32_e32 v22, v20, v21
	v_lshlrev_b32_e32 v49, 16, v114
	v_lshlrev_b32_e32 v48, 16, v110
	v_pk_mul_f32 v[20:21], v[44:45], v[44:45]
	v_lshlrev_b32_e32 v31, 16, v115
	v_lshlrev_b32_e32 v30, 16, v111
	v_pk_fma_f32 v[20:21], v[48:49], v[48:49], v[20:21]
	v_and_b32_e32 v29, 0xffff0000, v115
	v_and_b32_e32 v28, 0xffff0000, v111
	v_pk_fma_f32 v[20:21], v[30:31], v[30:31], v[20:21]
	v_lshlrev_b32_e32 v55, 16, v116
	v_lshlrev_b32_e32 v54, 16, v112
	v_pk_fma_f32 v[20:21], v[28:29], v[28:29], v[20:21]
	v_and_b32_e32 v53, 0xffff0000, v116
	v_and_b32_e32 v52, 0xffff0000, v112
	v_pk_fma_f32 v[20:21], v[54:55], v[54:55], v[20:21]
	v_lshlrev_b32_e32 v51, 16, v117
	v_lshlrev_b32_e32 v50, 16, v113
	v_pk_fma_f32 v[20:21], v[52:53], v[52:53], v[20:21]
	v_and_b32_e32 v47, 0xffff0000, v117
	v_and_b32_e32 v46, 0xffff0000, v113
	v_pk_fma_f32 v[20:21], v[50:51], v[50:51], v[20:21]
	s_nop 0
	v_pk_fma_f32 v[20:21], v[46:47], v[46:47], v[20:21]
	s_nop 0
	v_add_f32_e32 v20, v22, v20
	v_add_f32_e32 v20, v20, v21
	v_mov_b32_e32 v21, v20
	s_nop 1
	v_permlane32_swap_b32_e32 v20, v21
	v_add_f32_e32 v20, v20, v21
	v_fmamk_f32 v20, v20, 0x3c000000, v1
	v_cmp_gt_f32_e32 vcc, s33, v20
	v_mul_f32_e32 v21, 0x4b800000, v20
	s_nop 0
	v_cndmask_b32_e32 v20, v20, v21, vcc
	v_rsq_f32_e32 v20, v20
	s_nop 0
	v_mul_f32_e32 v21, 0x45800000, v20
	v_cndmask_b32_e32 v20, v20, v21, vcc
	v_mul_f32_e32 v92, 0x3dd53b94, v20
	ds_read_b128 v[20:23], v248 offset:16
	ds_read_b128 v[24:27], v248
	s_waitcnt lgkmcnt(0)
	v_mul_f32_e32 v20, v20, v92
	v_mul_f32_e32 v24, v24, v92
	v_mul_f32_e32 v25, v25, v92
	v_mul_f32_e32 v21, v21, v92
	v_mul_f32_e32 v26, v26, v92
	v_mul_f32_e32 v22, v22, v92
	v_mul_f32_e32 v27, v27, v92
	v_mul_f32_e32 v23, v23, v92
	v_mul_f32_e32 v24, v24, v107
	v_mul_f32_e32 v20, v20, v108
	v_mul_f32_e32 v25, v25, v105
	v_mul_f32_e32 v21, v21, v106
	v_mul_f32_e32 v26, v26, v102
	v_mul_f32_e32 v22, v22, v104
	v_mul_f32_e32 v27, v27, v98
	v_mul_f32_e32 v23, v23, v100
	v_cvt_pk_bf16_f32 v114, v24, v25
	v_cvt_pk_bf16_f32 v115, v26, v27
	v_cvt_pk_bf16_f32 v116, v20, v21
	v_cvt_pk_bf16_f32 v117, v22, v23
	ds_read_b128 v[20:23], v248 offset:80
	ds_read_b128 v[24:27], v248 offset:64
	v_and_b32_e32 v100, 0xffff0000, v4
	v_and_b32_e32 v98, 0xffff0000, v5
	s_waitcnt lgkmcnt(0)
	v_mul_f32_e32 v20, v20, v92
	v_mul_f32_e32 v24, v24, v92
	v_mul_f32_e32 v25, v25, v92
	v_mul_f32_e32 v21, v21, v92
	v_mul_f32_e32 v26, v26, v92
	v_mul_f32_e32 v22, v22, v92
	v_mul_f32_e32 v27, v27, v92
	v_mul_f32_e32 v23, v23, v92
	v_mul_f32_e32 v24, v24, v101
	v_mul_f32_e32 v20, v20, v103
	v_mul_f32_e32 v25, v25, v97
	v_mul_f32_e32 v21, v21, v99
	v_mul_f32_e32 v26, v26, v95
	v_mul_f32_e32 v22, v22, v96
	v_mul_f32_e32 v27, v27, v93
	v_mul_f32_e32 v23, v23, v94
	v_cvt_pk_bf16_f32 v118, v24, v25
	v_cvt_pk_bf16_f32 v119, v26, v27
	v_cvt_pk_bf16_f32 v120, v20, v21
	v_cvt_pk_bf16_f32 v121, v22, v23
	ds_read_b128 v[20:23], v248 offset:144
	ds_read_b128 v[24:27], v248 offset:128
	v_lshlrev_b32_e32 v96, 16, v5
	v_and_b32_e32 v101, 0xffff0000, v8
	v_mov_b32_e32 v103, v101
	v_lshlrev_b32_e32 v97, 16, v9
	v_and_b32_e32 v94, 0xffff0000, v6
	v_and_b32_e32 v99, 0xffff0000, v9
	v_lshlrev_b32_e32 v93, 16, v10
	v_and_b32_e32 v95, 0xffff0000, v10
	s_waitcnt lgkmcnt(0)
; __device__ __forceinline__ u32x4 pack8(const float* f) { u32x4 w; w.x = cvtpk(f[0], f[1]); w.y = cvtpk(f[2], f[3]); w.z = cvtpk(f[4], f[5]); w.w = cvtpk(f[6], f[7]); return w; }
; __device__ __forceinline__ bf16x8 pack8(const f32x4& a, const f32x4& b) { u32x4 w; w.x = cpk(a.x, a.y); w.y = cpk(a.z, a.w); w.z = cpk(b.x, b.y); w.w = cpk(b.z, b.w); return __builtin_bit_cast(bf16x8, w); }
; template <int VAR>
; __device__ __forceinline__ void attn_unit(const AUnit& u, LAS char* lds) {
;     ...
;         for (int d0 = 0; d0 < 8; ++d0) { float f[8]; unpack8(__builtin_bit_cast(u32x4, qr[d0]), f);
;             const f32x4 g0 = *(const f32x4*)(u.gqn + d0 * 16 + hi * 8), g1 = *(const f32x4*)(u.gqn + d0 * 16 + hi * 8 + 4);
; #pragma unroll
;             for (int e = 0; e < 4; ++e) { f[e] *= rn * g0[e]; f[4 + e] *= rn * g1[e]; }
;             qr[d0] = __builtin_bit_cast(bf16x8, pack8(f)); }
;         const int pos = u.pos0 + wq * 32 + r32;
; #pragma unroll
;         for (int a = 0; a < 2; ++a) { float x1[8], x2[8]; unpack8(__builtin_bit_cast(u32x4, qr[8 + a]), x1); unpack8(__builtin_bit_cast(u32x4, qr[10 + a]), x2);
;             const int i0 = a * 16 + hi * 8;
;             const f32x4 ga0 = *(const f32x4*)(u.gqr + i0), ga1 = *(const f32x4*)(u.gqr + i0 + 4), gb0 = *(const f32x4*)(u.gqr + 32 + i0), gb1 = *(const f32x4*)(u.gqr + 32 + i0 + 4);
	v_mul_f32_e32 v20, v92, v20
	v_mul_f32_e32 v24, v92, v24
	v_mul_f32_e32 v25, v92, v25
	v_mul_f32_e32 v21, v92, v21
	v_mul_f32_e32 v26, v92, v26
	v_mul_f32_e32 v22, v92, v22
	v_mul_f32_e32 v27, v92, v27
	v_mul_f32_e32 v23, v92, v23
	v_mul_f32_e32 v24, v24, v82
	v_mul_f32_e32 v20, v20, v86
	v_mul_f32_e32 v25, v25, v78
	v_mul_f32_e32 v21, v21, v84
	v_mul_f32_e32 v26, v26, v76
	v_mul_f32_e32 v22, v22, v80
	v_mul_f32_e32 v27, v27, v74
	v_mul_f32_e32 v23, v23, v72
	v_cvt_pk_bf16_f32 v122, v24, v25
	v_cvt_pk_bf16_f32 v123, v26, v27
	v_cvt_pk_bf16_f32 v124, v20, v21
	v_cvt_pk_bf16_f32 v125, v22, v23
	ds_read_b128 v[20:23], v248 offset:208
	ds_read_b128 v[24:27], v248 offset:192
	v_lshlrev_b32_e32 v78, 16, v12
	v_and_b32_e32 v12, 0xffff0000, v12
	v_and_b32_e32 v76, 0xffff0000, v13
	v_lshlrev_b32_e32 v84, 16, v7
	v_and_b32_e32 v86, 0xffff0000, v7
	v_mov_b32_e32 v5, v84
	v_mov_b32_e32 v7, v86
	s_waitcnt lgkmcnt(0)
	v_mul_f32_e32 v20, v92, v20
	v_mul_f32_e32 v24, v92, v24
	v_mul_f32_e32 v25, v92, v25
	v_mul_f32_e32 v21, v92, v21
	v_mul_f32_e32 v26, v92, v26
	v_mul_f32_e32 v22, v92, v22
	v_mul_f32_e32 v27, v92, v27
	v_mul_f32_e32 v23, v92, v23
	v_mul_f32_e32 v24, v24, v83
	v_mul_f32_e32 v20, v20, v87
	v_mul_f32_e32 v25, v25, v79
	v_mul_f32_e32 v21, v21, v85
	v_mul_f32_e32 v26, v26, v77
	v_mul_f32_e32 v22, v22, v81
	v_mul_f32_e32 v27, v27, v75
	v_mul_f32_e32 v23, v23, v73
	v_cvt_pk_bf16_f32 v126, v24, v25
	v_cvt_pk_bf16_f32 v127, v26, v27
	v_cvt_pk_bf16_f32 v128, v20, v21
	v_cvt_pk_bf16_f32 v129, v22, v23
	ds_read_b128 v[20:23], v248 offset:272
	ds_read_b128 v[24:27], v248 offset:256
	v_lshlrev_b32_e32 v79, 16, v16
	v_and_b32_e32 v77, 0xffff0000, v17
	v_lshlrev_b32_e32 v85, 16, v11
	v_and_b32_e32 v87, 0xffff0000, v11
	v_mov_b32_e32 v11, v94
	s_waitcnt lgkmcnt(0)
	v_mul_f32_e32 v20, v92, v20
	v_mul_f32_e32 v24, v92, v24
	v_mul_f32_e32 v25, v92, v25
	v_mul_f32_e32 v21, v92, v21
	v_mul_f32_e32 v26, v92, v26
	v_mul_f32_e32 v22, v92, v22
	v_mul_f32_e32 v27, v92, v27
	v_mul_f32_e32 v23, v92, v23
	v_mul_f32_e32 v24, v24, v68
	v_mul_f32_e32 v20, v20, v70
	v_mul_f32_e32 v25, v25, v64
	v_mul_f32_e32 v21, v21, v66
	v_mul_f32_e32 v26, v26, v60
	v_mul_f32_e32 v22, v22, v62
	v_mul_f32_e32 v27, v27, v58
	v_mul_f32_e32 v23, v23, v56
	v_cvt_pk_bf16_f32 v130, v24, v25
	v_cvt_pk_bf16_f32 v131, v26, v27
	v_cvt_pk_bf16_f32 v132, v20, v21
	v_cvt_pk_bf16_f32 v133, v22, v23
	ds_read_b128 v[20:23], v248 offset:336
	ds_read_b128 v[24:27], v248 offset:320
	v_lshlrev_b32_e32 v64, 16, v15
	v_and_b32_e32 v68, 0xffff0000, v15
	v_and_b32_e32 v15, 0xffff0000, v18
	v_lshlrev_b32_e32 v70, 16, v14
	v_and_b32_e32 v14, 0xffff0000, v14
	v_mov_b32_e32 v10, v14
	s_waitcnt lgkmcnt(0)
	v_mul_f32_e32 v20, v92, v20
	v_mul_f32_e32 v24, v92, v24
	v_mul_f32_e32 v25, v92, v25
	v_mul_f32_e32 v21, v92, v21
	v_mul_f32_e32 v26, v92, v26
	v_mul_f32_e32 v22, v92, v22
	v_mul_f32_e32 v27, v92, v27
	v_mul_f32_e32 v23, v92, v23
	v_mul_f32_e32 v24, v24, v69
	v_mul_f32_e32 v20, v20, v71
	v_mul_f32_e32 v25, v25, v65
	v_mul_f32_e32 v21, v21, v67
	v_mul_f32_e32 v26, v26, v61
	v_mul_f32_e32 v22, v22, v63
	v_mul_f32_e32 v27, v27, v59
	v_mul_f32_e32 v23, v23, v57
	v_cvt_pk_bf16_f32 v134, v24, v25
	v_cvt_pk_bf16_f32 v135, v26, v27
	v_cvt_pk_bf16_f32 v136, v20, v21
	v_cvt_pk_bf16_f32 v137, v22, v23
	ds_read_b128 v[20:23], v248 offset:400
	ds_read_b128 v[24:27], v248 offset:384
	v_lshlrev_b32_e32 v71, 16, v18
	v_lshlrev_b32_e32 v18, 16, v13
	v_and_b32_e32 v13, 0xffff0000, v16
	v_add_u32_e32 v16, 0x10010, v43
	v_lshlrev_b32_e32 v65, 16, v19
	v_and_b32_e32 v69, 0xffff0000, v19
	v_lshlrev_b32_e32 v19, 16, v17
	v_ashrrev_i32_e32 v17, 31, v16
	v_lshl_add_u64 v[82:83], v[16:17], 3, s[6:7]
	v_mov_b32_e32 v16, v18
	v_mov_b32_e32 v17, v96
	v_mov_b32_e32 v102, v13
	v_pk_mul_f32 v[102:103], v[102:103], v[102:103]
	s_waitcnt lgkmcnt(0)
	v_mul_f32_e32 v20, v92, v20
	v_mul_f32_e32 v24, v92, v24
	v_mul_f32_e32 v25, v92, v25
	v_mul_f32_e32 v21, v92, v21
	v_mul_f32_e32 v26, v92, v26
	v_mul_f32_e32 v22, v92, v22
	v_mul_f32_e32 v27, v92, v27
	v_mul_f32_e32 v23, v92, v23
	v_mul_f32_e32 v24, v24, v48
	v_mul_f32_e32 v20, v20, v54
	v_mul_f32_e32 v25, v25, v44
	v_mul_f32_e32 v21, v21, v52
	v_mul_f32_e32 v26, v26, v30
	v_mul_f32_e32 v22, v22, v50
	v_mul_f32_e32 v27, v27, v28
	v_mul_f32_e32 v23, v23, v46
	v_cvt_pk_bf16_f32 v138, v24, v25
	v_cvt_pk_bf16_f32 v139, v26, v27
	v_cvt_pk_bf16_f32 v140, v20, v21
	v_cvt_pk_bf16_f32 v141, v22, v23
	ds_read_b128 v[20:23], v248 offset:464
	ds_read_b128 v[24:27], v248 offset:448
	v_add_u32_e32 v48, 0x10000, v43
	s_waitcnt lgkmcnt(0)
	v_mul_f32_e32 v20, v92, v20
	v_mul_f32_e32 v24, v92, v24
	v_mul_f32_e32 v25, v92, v25
	v_mul_f32_e32 v21, v92, v21
	v_mul_f32_e32 v26, v92, v26
	v_mul_f32_e32 v22, v92, v22
	v_mul_f32_e32 v27, v92, v27
	v_mul_f32_e32 v23, v92, v23
	v_mul_f32_e32 v24, v24, v49
	v_mul_f32_e32 v20, v20, v55
	v_mul_f32_e32 v25, v25, v45
	v_mul_f32_e32 v21, v21, v53
	v_mul_f32_e32 v26, v26, v31
	v_mul_f32_e32 v22, v22, v51
	v_mul_f32_e32 v27, v27, v29
	v_mul_f32_e32 v23, v23, v47
	v_cvt_pk_bf16_f32 v142, v24, v25
	v_cvt_pk_bf16_f32 v143, v26, v27
	v_cvt_pk_bf16_f32 v144, v20, v21
	v_cvt_pk_bf16_f32 v145, v22, v23
	ds_read_b128 v[20:23], v248 offset:512
	ds_read_b128 v[24:27], v248 offset:528
	ds_read_b128 v[28:31], v248 offset:640
	ds_read_b128 v[44:47], v248 offset:656
	v_ashrrev_i32_e32 v49, 31, v48
	v_lshl_add_u64 v[60:61], v[48:49], 3, s[6:7]
	global_load_dwordx4 v[48:51], v[60:61], off offset:48
	global_load_dwordx4 v[52:55], v[60:61], off offset:32
	global_load_dwordx4 v[56:59], v[60:61], off offset:16
	s_nop 0
	global_load_dwordx4 v[60:63], v[60:61], off
	v_lshlrev_b32_e32 v92, 16, v6
	v_mov_b32_e32 v9, v92
	v_mov_b32_e32 v6, v68
	s_waitcnt vmcnt(0)
; __device__ __forceinline__ u32x4 pack8(const float* f) { u32x4 w; w.x = cvtpk(f[0], f[1]); w.y = cvtpk(f[2], f[3]); w.z = cvtpk(f[4], f[5]); w.w = cvtpk(f[6], f[7]); return w; }
; __device__ __forceinline__ bf16x8 pack8(const f32x4& a, const f32x4& b) { u32x4 w; w.x = cpk(a.x, a.y); w.y = cpk(a.z, a.w); w.z = cpk(b.x, b.y); w.w = cpk(b.z, b.w); return __builtin_bit_cast(bf16x8, w); }
; template <int VAR>
; __device__ __forceinline__ void attn_unit(const AUnit& u, LAS char* lds) {
;     ...
;         const int pos = u.pos0 + wq * 32 + r32;
; #pragma unroll
;         for (int a = 0; a < 2; ++a) { float x1[8], x2[8]; unpack8(__builtin_bit_cast(u32x4, qr[8 + a]), x1); unpack8(__builtin_bit_cast(u32x4, qr[10 + a]), x2);
;             const int i0 = a * 16 + hi * 8;
;             const f32x4 ga0 = *(const f32x4*)(u.gqr + i0), ga1 = *(const f32x4*)(u.gqr + i0 + 4), gb0 = *(const f32x4*)(u.gqr + 32 + i0), gb1 = *(const f32x4*)(u.gqr + 32 + i0 + 4);
;             float y1[8], y2[8];
; #pragma unroll
;             for (int e = 0; e < 8; ++e) { const float v1 = x1[e] * rr_ * (e < 4 ? ga0[e & 3] : ga1[e & 3]), v2 = x2[e] * rr_ * (e < 4 ? gb0[e & 3] : gb1[e & 3]);
;                 const float2 cs = u.tab[pos * 32 + i0 + e];
;                 y1[e] = (v1 * cs.x - v2 * cs.y) * QSCALE; y2[e] = (v2 * cs.x + v1 * cs.y) * QSCALE; }
;             qr[8 + a] = __builtin_bit_cast(bf16x8, pack8(y1)); qr[10 + a] = __builtin_bit_cast(bf16x8, pack8(y2)); }
	s_waitcnt lgkmcnt(0)
	v_mov_b32_e32 v80, v20
	v_mov_b32_e32 v66, v26
	v_lshlrev_b32_e32 v20, 16, v4
	v_mov_b32_e32 v67, v46
	v_mov_b32_e32 v46, v27
	v_mov_b32_e32 v26, v12
	v_mov_b32_e32 v27, v100
	v_mov_b32_e32 v72, v24
	v_mov_b32_e32 v73, v44
	v_mov_b32_e32 v44, v25
	v_mov_b32_e32 v24, v78
	v_mov_b32_e32 v25, v20
	v_pk_mul_f32 v[26:27], v[26:27], v[26:27]
	v_mov_b32_e32 v81, v28
	v_mov_b32_e32 v28, v21
	v_lshlrev_b32_e32 v21, 16, v8
	v_pk_fma_f32 v[24:25], v[24:25], v[24:25], v[26:27]
	v_mov_b32_e32 v74, v22
	v_mov_b32_e32 v75, v30
	v_mov_b32_e32 v30, v23
	v_mov_b32_e32 v22, v76
	v_mov_b32_e32 v23, v98
	v_pk_fma_f32 v[16:17], v[16:17], v[16:17], v[24:25]
	v_mov_b32_e32 v26, v79
	v_mov_b32_e32 v27, v21
	v_mov_b32_e32 v8, v70
	v_pk_fma_f32 v[16:17], v[22:23], v[22:23], v[16:17]
	v_mov_b32_e32 v22, v19
	v_mov_b32_e32 v23, v97
	v_pk_fma_f32 v[26:27], v[26:27], v[26:27], v[102:103]
	v_pk_fma_f32 v[8:9], v[8:9], v[8:9], v[16:17]
	v_mov_b32_e32 v24, v77
	v_mov_b32_e32 v25, v99
	v_pk_fma_f32 v[22:23], v[22:23], v[22:23], v[26:27]
	v_mov_b32_e32 v4, v64
	v_pk_fma_f32 v[8:9], v[10:11], v[10:11], v[8:9]
	v_mov_b32_e32 v10, v71
	v_mov_b32_e32 v11, v93
	v_pk_fma_f32 v[22:23], v[24:25], v[24:25], v[22:23]
	v_pk_fma_f32 v[4:5], v[4:5], v[4:5], v[8:9]
	v_mov_b32_e32 v16, v15
	v_mov_b32_e32 v17, v95
	v_pk_fma_f32 v[10:11], v[10:11], v[10:11], v[22:23]
	v_pk_fma_f32 v[4:5], v[6:7], v[6:7], v[4:5]
	v_mov_b32_e32 v6, v65
	v_mov_b32_e32 v7, v85
	v_pk_fma_f32 v[10:11], v[16:17], v[16:17], v[10:11]
	v_mov_b32_e32 v8, v69
	v_mov_b32_e32 v9, v87
	v_pk_fma_f32 v[6:7], v[6:7], v[6:7], v[10:11]
	v_pk_add_f32 v[4:5], v[4:5], v[4:5] op_sel:[0,1] op_sel_hi:[1,0]
	v_pk_fma_f32 v[6:7], v[8:9], v[8:9], v[6:7]
	s_nop 0
	v_pk_add_f32 v[4:5], v[4:5], v[6:7]
	s_nop 0
	v_pk_add_f32 v[4:5], v[4:5], v[6:7] op_sel:[0,1] op_sel_hi:[1,0]
	s_nop 0
	v_mov_b32_e32 v5, v4
	s_nop 1
	v_permlane32_swap_b32_e32 v4, v5
	v_add_f32_e32 v4, v4, v5
	v_fmamk_f32 v4, v4, 0x3c800000, v1
	v_cmp_gt_f32_e32 vcc, s33, v4
	v_mul_f32_e32 v5, 0x4b800000, v4
	s_nop 0
	v_cndmask_b32_e32 v4, v4, v5, vcc
	v_rsq_f32_e32 v4, v4
	s_nop 0
	v_mul_f32_e32 v5, 0x45800000, v4
	v_cndmask_b32_e32 v102, v4, v5, vcc
	v_pk_mul_f32 v[4:5], v[102:103], v[78:79] op_sel_hi:[0,1]
	v_pk_mul_f32 v[4:5], v[4:5], v[80:81]
	v_pk_mul_f32 v[20:21], v[102:103], v[20:21] op_sel_hi:[0,1]
	v_pk_mul_f32 v[6:7], v[4:5], v[60:61]
	v_pk_mul_f32 v[4:5], v[4:5], v[60:61] op_sel:[1,0] op_sel_hi:[0,1]
	v_add_f32_e32 v4, v4, v5
	v_mul_f32_e32 v9, 0x3dd53b94, v4
	v_pk_mul_f32 v[4:5], v[102:103], v[12:13] op_sel_hi:[0,1]
	v_sub_f32_e32 v6, v6, v7
	v_pk_mul_f32 v[4:5], v[4:5], v[28:29]
	v_mul_f32_e32 v8, 0x3dd53b94, v6
	v_pk_mul_f32 v[6:7], v[4:5], v[62:63]
	v_pk_mul_f32 v[4:5], v[4:5], v[62:63] op_sel:[1,0] op_sel_hi:[0,1]
	v_add_f32_e32 v4, v4, v5
	v_mul_f32_e32 v11, 0x3dd53b94, v4
	v_pk_mul_f32 v[4:5], v[102:103], v[18:19] op_sel_hi:[0,1]
	v_sub_f32_e32 v6, v6, v7
	v_pk_mul_f32 v[4:5], v[4:5], v[74:75]
	v_mul_f32_e32 v10, 0x3dd53b94, v6
	v_pk_mul_f32 v[6:7], v[4:5], v[56:57]
	v_pk_mul_f32 v[4:5], v[4:5], v[56:57] op_sel:[1,0] op_sel_hi:[0,1]
	v_add_f32_e32 v4, v4, v5
	v_mul_f32_e32 v13, 0x3dd53b94, v4
	v_pk_mul_f32 v[4:5], v[102:103], v[76:77] op_sel_hi:[0,1]
	v_sub_f32_e32 v6, v6, v7
	v_pk_mul_f32 v[4:5], v[4:5], v[30:31]
	v_mul_f32_e32 v12, 0x3dd53b94, v6
	v_pk_mul_f32 v[6:7], v[4:5], v[58:59]
	v_pk_mul_f32 v[4:5], v[4:5], v[58:59] op_sel:[1,0] op_sel_hi:[0,1]
	v_add_f32_e32 v4, v4, v5
	v_mul_f32_e32 v17, 0x3dd53b94, v4
	v_pk_mul_f32 v[4:5], v[102:103], v[70:71] op_sel_hi:[0,1]
	v_sub_f32_e32 v6, v6, v7
	v_pk_mul_f32 v[4:5], v[4:5], v[72:73]
	v_mul_f32_e32 v16, 0x3dd53b94, v6
	v_pk_mul_f32 v[6:7], v[4:5], v[52:53]
	v_pk_mul_f32 v[4:5], v[4:5], v[52:53] op_sel:[1,0] op_sel_hi:[0,1]
	v_add_f32_e32 v4, v4, v5
	v_mul_f32_e32 v19, 0x3dd53b94, v4
	v_pk_mul_f32 v[4:5], v[102:103], v[14:15] op_sel_hi:[0,1]
	v_sub_f32_e32 v6, v6, v7
	v_pk_mul_f32 v[4:5], v[4:5], v[44:45]
	v_mul_f32_e32 v18, 0x3dd53b94, v6
	v_pk_mul_f32 v[6:7], v[4:5], v[54:55]
	v_pk_mul_f32 v[4:5], v[4:5], v[54:55] op_sel:[1,0] op_sel_hi:[0,1]
	v_add_f32_e32 v4, v4, v5
	v_mul_f32_e32 v15, 0x3dd53b94, v4
	v_pk_mul_f32 v[4:5], v[102:103], v[64:65] op_sel_hi:[0,1]
	v_sub_f32_e32 v6, v6, v7
	v_pk_mul_f32 v[4:5], v[4:5], v[66:67]
	v_mul_f32_e32 v14, 0x3dd53b94, v6
	v_pk_mul_f32 v[6:7], v[4:5], v[48:49]
	v_pk_mul_f32 v[4:5], v[4:5], v[48:49] op_sel:[1,0] op_sel_hi:[0,1]
	v_add_f32_e32 v4, v4, v5
	v_mul_f32_e32 v23, 0x3dd53b94, v4
	v_pk_mul_f32 v[4:5], v[102:103], v[68:69] op_sel_hi:[0,1]
	v_sub_f32_e32 v6, v6, v7
	v_pk_mul_f32 v[4:5], v[4:5], v[46:47]
	v_mul_f32_e32 v22, 0x3dd53b94, v6
	v_pk_mul_f32 v[6:7], v[4:5], v[50:51]
	v_pk_mul_f32 v[4:5], v[4:5], v[50:51] op_sel:[1,0] op_sel_hi:[0,1]
	v_sub_f32_e32 v6, v6, v7
	v_add_f32_e32 v4, v4, v5
	v_mul_f32_e32 v6, 0x3dd53b94, v6
	v_mul_f32_e32 v4, 0x3dd53b94, v4
	v_cvt_pk_bf16_f32 v146, v8, v10
	v_cvt_pk_bf16_f32 v147, v12, v16
	v_cvt_pk_bf16_f32 v148, v18, v14
	v_cvt_pk_bf16_f32 v149, v22, v6
	v_cvt_pk_bf16_f32 v150, v9, v11
	v_cvt_pk_bf16_f32 v151, v13, v17
	v_cvt_pk_bf16_f32 v152, v19, v15
	v_cvt_pk_bf16_f32 v153, v23, v4
	ds_read_b128 v[4:7], v248 offset:592
	ds_read_b128 v[8:11], v248 offset:576
	ds_read_b128 v[12:15], v248 offset:720
	ds_read_b128 v[16:19], v248 offset:704
	s_waitcnt lgkmcnt(0)
	v_mov_b32_e32 v22, v8
	v_mov_b32_e32 v23, v16
	v_pk_mul_f32 v[48:49], v[20:21], v[22:23]
	global_load_dwordx4 v[20:23], v[82:83], off offset:48
	global_load_dwordx4 v[24:27], v[82:83], off offset:32
	global_load_dwordx4 v[28:31], v[82:83], off offset:16
	global_load_dwordx4 v[44:47], v[82:83], off
	v_mov_b32_e32 v16, v9
	s_waitcnt vmcnt(0)
; #define LAS __attribute__((address_space(3)))
; __device__ __forceinline__ u32x4 pack8(const float* f) { u32x4 w; w.x = cvtpk(f[0], f[1]); w.y = cvtpk(f[2], f[3]); w.z = cvtpk(f[4], f[5]); w.w = cvtpk(f[6], f[7]); return w; }
; __device__ __forceinline__ int v_rd_base(int lane) { return ((lane & 3) << 3) | (((lane >> 2) & 3) << 6) | (((lane >> 4) & 1) << 5) | (((lane >> 5) & 1) << 8); }
; #define AWAITV() asm volatile("s_waitcnt vmcnt(0)" ::: "memory")
; __device__ __forceinline__ bf16x8 pack8(const f32x4& a, const f32x4& b) { u32x4 w; w.x = cpk(a.x, a.y); w.y = cpk(a.z, a.w); w.z = cpk(b.x, b.y); w.w = cpk(b.z, b.w); return __builtin_bit_cast(bf16x8, w); }
; template <int VAR>
; __device__ __forceinline__ void attn_unit(const AUnit& u, LAS char* lds) {
;     ...
; #pragma unroll
;         for (int a = 0; a < 2; ++a) { float x1[8], x2[8]; unpack8(__builtin_bit_cast(u32x4, qr[8 + a]), x1); unpack8(__builtin_bit_cast(u32x4, qr[10 + a]), x2);
;             const int i0 = a * 16 + hi * 8;
;             const f32x4 ga0 = *(const f32x4*)(u.gqr + i0), ga1 = *(const f32x4*)(u.gqr + i0 + 4), gb0 = *(const f32x4*)(u.gqr + 32 + i0), gb1 = *(const f32x4*)(u.gqr + 32 + i0 + 4);
;             float y1[8], y2[8];
; #pragma unroll
;             for (int e = 0; e < 8; ++e) { const float v1 = x1[e] * rr_ * (e < 4 ? ga0[e & 3] : ga1[e & 3]), v2 = x2[e] * rr_ * (e < 4 ? gb0[e & 3] : gb1[e & 3]);
;                 const float2 cs = u.tab[pos * 32 + i0 + e];
;                 y1[e] = (v1 * cs.x - v2 * cs.y) * QSCALE; y2[e] = (v2 * cs.x + v1 * cs.y) * QSCALE; }
;             qr[8 + a] = __builtin_bit_cast(bf16x8, pack8(y1)); qr[10 + a] = __builtin_bit_cast(bf16x8, pack8(y2)); }
;     }
;     float m_reg = -1e30f, l_reg = 0.f; f32x16 o[4]; o[0] = f32x16{}; o[1] = f32x16{}; o[2] = f32x16{}; o[3] = f32x16{};
;     LAS float* wsf = (LAS float*)(lds + OFF_WS) + wid * 64; LAS float* li_l = wsf; LAS float* al_l = wsf + 32;
;     const int vb0 = (int)(unsigned)(uintptr_t)lds + v_rd_base(lane);
;     AWAITV();
;     __syncthreads();
	v_pk_mul_f32 v[50:51], v[48:49], v[44:45]
	s_nop 0
	v_sub_f32_e32 v8, v50, v51
	v_pk_mul_f32 v[44:45], v[48:49], v[44:45] op_sel:[1,0] op_sel_hi:[0,1]
	v_mul_f32_e32 v43, 0x3dd53b94, v8
	v_add_f32_e32 v8, v44, v45
	v_pk_mul_f32 v[44:45], v[102:103], v[100:101] op_sel_hi:[0,1]
	v_mul_f32_e32 v48, 0x3dd53b94, v8
	v_pk_mul_f32 v[8:9], v[44:45], v[16:17]
	s_nop 0
	v_pk_mul_f32 v[16:17], v[8:9], v[46:47]
	v_pk_mul_f32 v[8:9], v[8:9], v[46:47] op_sel:[1,0] op_sel_hi:[0,1]
	v_sub_f32_e32 v16, v16, v17
	v_add_f32_e32 v8, v8, v9
	v_mul_f32_e32 v44, 0x3dd53b94, v16
	v_mul_f32_e32 v45, 0x3dd53b94, v8
	v_pk_mul_f32 v[8:9], v[102:103], v[96:97] op_sel_hi:[0,1]
	v_mov_b32_e32 v16, v10
	v_mov_b32_e32 v17, v18
	v_pk_mul_f32 v[8:9], v[8:9], v[16:17]
	v_mov_b32_e32 v18, v11
	v_pk_mul_f32 v[16:17], v[8:9], v[28:29]
	v_pk_mul_f32 v[8:9], v[8:9], v[28:29] op_sel:[1,0] op_sel_hi:[0,1]
	v_add_f32_e32 v8, v8, v9
	v_sub_f32_e32 v10, v16, v17
	v_mul_f32_e32 v17, 0x3dd53b94, v8
	v_pk_mul_f32 v[8:9], v[102:103], v[98:99] op_sel_hi:[0,1]
	v_pk_mul_f32 v[8:9], v[8:9], v[18:19]
	v_mul_f32_e32 v16, 0x3dd53b94, v10
	v_pk_mul_f32 v[10:11], v[8:9], v[30:31]
	v_pk_mul_f32 v[8:9], v[8:9], v[30:31] op_sel:[1,0] op_sel_hi:[0,1]
	v_sub_f32_e32 v10, v10, v11
	v_add_f32_e32 v8, v8, v9
	v_mul_f32_e32 v18, 0x3dd53b94, v10
	v_mul_f32_e32 v19, 0x3dd53b94, v8
	v_pk_mul_f32 v[8:9], v[102:103], v[92:93] op_sel_hi:[0,1]
	v_mov_b32_e32 v10, v4
	v_mov_b32_e32 v11, v12
	v_pk_mul_f32 v[8:9], v[8:9], v[10:11]
	v_mov_b32_e32 v12, v5
	v_pk_mul_f32 v[10:11], v[8:9], v[24:25]
	v_pk_mul_f32 v[8:9], v[8:9], v[24:25] op_sel:[1,0] op_sel_hi:[0,1]
	v_sub_f32_e32 v4, v10, v11
	v_mul_f32_e32 v10, 0x3dd53b94, v4
	v_add_f32_e32 v4, v8, v9
	v_pk_mul_f32 v[8:9], v[102:103], v[94:95] op_sel_hi:[0,1]
	v_mul_f32_e32 v11, 0x3dd53b94, v4
	v_pk_mul_f32 v[4:5], v[8:9], v[12:13]
	v_cvt_pk_bf16_f32 v154, v43, v44
	v_cvt_pk_bf16_f32 v155, v16, v18
	v_mov_b32_e32 v16, v3
	v_pk_mul_f32 v[8:9], v[4:5], v[26:27]
	v_pk_mul_f32 v[4:5], v[4:5], v[26:27] op_sel:[1,0] op_sel_hi:[0,1]
	v_sub_f32_e32 v8, v8, v9
	v_add_f32_e32 v4, v4, v5
	v_mul_f32_e32 v12, 0x3dd53b94, v8
	v_mul_f32_e32 v13, 0x3dd53b94, v4
	v_pk_mul_f32 v[4:5], v[102:103], v[84:85] op_sel_hi:[0,1]
	v_mov_b32_e32 v8, v6
	v_mov_b32_e32 v9, v14
	v_pk_mul_f32 v[4:5], v[4:5], v[8:9]
	v_mov_b32_e32 v14, v7
	v_pk_mul_f32 v[8:9], v[4:5], v[20:21]
	v_pk_mul_f32 v[4:5], v[4:5], v[20:21] op_sel:[1,0] op_sel_hi:[0,1]
	v_add_f32_e32 v4, v4, v5
	v_sub_f32_e32 v6, v8, v9
	v_mul_f32_e32 v9, 0x3dd53b94, v4
	v_pk_mul_f32 v[4:5], v[102:103], v[86:87] op_sel_hi:[0,1]
	v_pk_mul_f32 v[4:5], v[4:5], v[14:15]
	v_mul_f32_e32 v8, 0x3dd53b94, v6
	v_pk_mul_f32 v[6:7], v[4:5], v[22:23]
	v_pk_mul_f32 v[4:5], v[4:5], v[22:23] op_sel:[1,0] op_sel_hi:[0,1]
	v_sub_f32_e32 v6, v6, v7
	v_add_f32_e32 v4, v4, v5
	v_mul_f32_e32 v6, 0x3dd53b94, v6
	v_mul_f32_e32 v4, 0x3dd53b94, v4
	v_lshlrev_b32_e32 v5, 4, v181
	v_cvt_pk_bf16_f32 v156, v10, v12
	v_cvt_pk_bf16_f32 v157, v8, v6
	v_cvt_pk_bf16_f32 v158, v48, v45
	v_cvt_pk_bf16_f32 v159, v17, v19
	v_cvt_pk_bf16_f32 v160, v11, v13
	v_cvt_pk_bf16_f32 v161, v9, v4
	v_lshlrev_b32_e32 v4, 3, v88
	v_and_b32_e32 v6, 0xc0, v5
	v_lshlrev_b32_e32 v7, 1, v181
	v_and_or_b32 v6, v4, 24, v6
	v_and_b32_e32 v7, 32, v7
	v_and_b32_e32 v4, 0x100, v4
	v_or3_b32 v4, v6, v7, v4
	v_add_u32_e32 v163, 0, v4
	v_and_b32_e32 v4, 0xf0, v5
	v_bitop3_b32 v185, v162, v4, 32 bitop3:0x36
	v_bitop3_b32 v186, v162, v4, 64 bitop3:0x36
	v_bitop3_b32 v187, v162, v4, s24 bitop3:0x36
	v_bitop3_b32 v207, v162, v4, s23 bitop3:0x36
	v_bitop3_b32 v208, v162, v4, s25 bitop3:0x36
	v_bitop3_b32 v209, v162, v4, s14 bitop3:0x36
	v_bitop3_b32 v210, v162, v4, s15 bitop3:0x36
	v_lshlrev_b32_e32 v4, 7, v180
	v_add_u32_e32 v224, s10, v4
	s_mul_i32 s10, s4, 0x82000
	s_add_u32 s48, s58, s10
	v_bitop3_b32 v184, v162, v5, s20 bitop3:0x78
	v_and_b32_e32 v5, 0x70, v89
	s_addc_u32 s49, 0, s5
	v_sub_u32_e32 v211, v183, v4
	v_bitop3_b32 v213, v162, v5, 32 bitop3:0x36
	v_bitop3_b32 v214, v162, v5, 64 bitop3:0x36
	v_bitop3_b32 v215, v162, v5, s24 bitop3:0x36
	v_lshl_add_u64 v[4:5], s[48:49], 0, v[38:39]
	v_readlane_b32 s58, v252, 12
	v_or_b32_e32 v4, v4, v42
	v_readlane_b32 s59, v252, 13
	v_bitop3_b32 v6, v32, 15, v181 bitop3:0x48
	s_waitcnt vmcnt(0)
	v_mov_b32_e32 v17, v3
	v_lshl_add_u64 v[172:173], s[58:59], 0, v[4:5]
	v_lshl_add_u64 v[4:5], s[48:49], 0, v[34:35]
	v_lshl_or_b32 v4, v6, 4, v4
	v_lshl_add_u64 v[174:175], s[58:59], 0, v[4:5]
	v_mad_i64_i32 v[4:5], s[4:5], s4, v204, v[36:37]
	v_bitop3_b32 v6, v33, 7, v181 bitop3:0x48
	v_lshl_or_b32 v4, v6, 4, v4
	v_lshl_add_u64 v[176:177], s[58:59], 0, v[4:5]
	v_lshl_add_u64 v[4:5], s[48:49], 0, v[40:41]
	v_or_b32_e32 v4, v4, v2
	v_lshl_add_u64 v[178:179], s[58:59], 0, v[4:5]
	v_mov_b32_e32 v2, v3
	v_mov_b32_e32 v4, v3
	v_mov_b32_e32 v5, v3
	v_mov_b32_e32 v6, v3
	v_mov_b32_e32 v7, v3
	v_mov_b32_e32 v8, v3
	v_mov_b32_e32 v9, v3
	v_mov_b32_e32 v10, v3
	v_mov_b32_e32 v11, v3
	v_mov_b32_e32 v12, v3
	v_mov_b32_e32 v13, v3
	v_mov_b32_e32 v14, v3
	v_mov_b32_e32 v15, v3
	v_mov_b64_e32 v[32:33], v[16:17]
	v_mov_b64_e32 v[48:49], v[16:17]
	v_mov_b64_e32 v[64:65], v[16:17]
	v_mov_b64_e32 v[80:81], v[16:17]
	v_add3_u32 v216, v183, v184, s22
	v_add3_u32 v217, v183, v185, s22
	v_add3_u32 v218, v183, v186, s22
	v_add3_u32 v219, v183, v187, s22
	v_add3_u32 v220, v183, v207, s22
	v_add3_u32 v221, v183, v208, s22
	v_add3_u32 v222, v183, v209, s22
	v_add3_u32 v223, v183, v210, s22
	s_mov_b32 s4, -2
	v_mov_b64_e32 v[30:31], v[14:15]
	v_mov_b64_e32 v[28:29], v[12:13]
	v_mov_b64_e32 v[26:27], v[10:11]
	v_mov_b64_e32 v[24:25], v[8:9]
	v_mov_b64_e32 v[22:23], v[6:7]
	v_mov_b64_e32 v[20:21], v[4:5]
	v_mov_b64_e32 v[18:19], v[2:3]
	v_mov_b64_e32 v[46:47], v[14:15]
	v_mov_b64_e32 v[44:45], v[12:13]
	v_mov_b64_e32 v[42:43], v[10:11]
	v_mov_b64_e32 v[40:41], v[8:9]
	v_mov_b64_e32 v[38:39], v[6:7]
	v_mov_b64_e32 v[36:37], v[4:5]
	v_mov_b64_e32 v[34:35], v[2:3]
	v_mov_b64_e32 v[62:63], v[14:15]
	v_mov_b64_e32 v[60:61], v[12:13]
	v_mov_b64_e32 v[58:59], v[10:11]
	v_mov_b64_e32 v[56:57], v[8:9]
	v_mov_b64_e32 v[54:55], v[6:7]
	v_mov_b64_e32 v[52:53], v[4:5]
	v_mov_b64_e32 v[50:51], v[2:3]
	v_mov_b64_e32 v[78:79], v[14:15]
	v_mov_b64_e32 v[76:77], v[12:13]
	v_mov_b64_e32 v[74:75], v[10:11]
	v_mov_b64_e32 v[72:73], v[8:9]
	v_mov_b64_e32 v[70:71], v[6:7]
	v_mov_b64_e32 v[68:69], v[4:5]
	v_mov_b64_e32 v[66:67], v[2:3]
	s_waitcnt lgkmcnt(0)
	s_barrier
